# split-K sample-row pieces run before the main GEMM tile of phases 2/9/11/14/17 instead of after its epilogue
# baseline (speedup 1.0000x reference)
.LBB0_321:
	s_cmp_lt_i32 s30, 3
	s_cselect_b64 s[8:9], -1, 0
	s_add_u32 s56, s28, 0xe600000
	s_addc_u32 s57, s29, 0
	s_add_u32 s54, s28, 0x2ec00000
	s_addc_u32 s55, s29, 0
	s_and_b64 s[8:9], s[8:9], s[6:7]
	s_andn2_b64 vcc, exec, s[8:9]
	v_bfe_u32 v234, v231, 2, 4
	v_bfe_u32 v235, v231, 2, 2
	v_and_b32_e32 v232, 15, v231
	v_and_b32_e32 v239, 32, v231
	v_and_b32_e32 v139, 64, v231
	v_lshrrev_b32_e32 v237, 5, v231
	v_lshrrev_b32_e32 v238, 1, v231
	v_lshrrev_b32_e32 v236, 3, v231
	v_lshlrev_b32_e32 v233, 6, v231
	v_lshlrev_b32_e32 v138, 2, v231
	s_cbranch_vccnz .LBB0_358
	s_cmpk_gt_i32 s2, 0xaf
	s_cbranch_scc1 .Lmain_2
	v_and_b32_e32 v64, 63, v231
	v_and_b32_e32 v65, 15, v64
	v_bfe_u32 v66, v64, 4, 2
	v_readfirstlane_b32 s44, v230
	s_and_b32 s60, s2, 7
	s_lshr_b32 s61, s2, 3
	s_lshl_b32 s63, s61, 9
	s_nop 0
	s_and_b32 s40, s44, 3
	s_lshr_b32 s59, s44, 2
	v_and_b32_e32 v67, 3, v65
	v_xor_b32_e32 v67, v66, v67
	v_lshlrev_b32_e32 v67, 4, v67
	v_lshl_add_u32 v67, v65, 9, v67
	v_lshrrev_b32_e32 v69, 2, v65
	s_lshl_b32 s64, s40, 14
	s_lshl_b32 s76, s59, 15
	s_add_u32 s76, s76, 0x10000
	v_xor_b32_e32 v70, 0, v69
	v_lshl_add_u32 v70, v70, 6, v67
	v_add_u32_e32 v74, s76, v70
	v_add_u32_e32 v70, s64, v70
	v_xor_b32_e32 v71, 1, v69
	v_lshl_add_u32 v71, v71, 6, v67
	v_add_u32_e32 v75, s76, v71
	v_add_u32_e32 v71, s64, v71
	v_xor_b32_e32 v72, 2, v69
	v_lshl_add_u32 v72, v72, 6, v67
	v_add_u32_e32 v76, s76, v72
	v_add_u32_e32 v72, s64, v72
	v_xor_b32_e32 v73, 3, v69
	v_lshl_add_u32 v73, v73, 6, v67
	v_add_u32_e32 v77, s76, v73
	v_add_u32_e32 v73, s64, v73
	v_lshrrev_b32_e32 v68, 5, v64
	s_lshl_b32 s77, s44, 1
	v_add_u32_e32 v69, s77, v68
	v_and_b32_e32 v67, 31, v64
	v_xor_b32_e32 v67, v67, v69
	v_lshlrev_b32_e32 v67, 4, v67
	v_mul_u32_u24_e32 v68, 0x2c00, v68
	v_add_u32_e32 v68, v68, v67
	v_lshlrev_b32_e32 v69, 13, v65
	v_lshl_add_u32 v69, v66, 4, v69
	s_lshl_b32 s62, s44, 1
	s_mul_i32 s62, s62, 0x2c00
	s_add_u32 s14, s28, 0x1d300000
	s_addc_u32 s15, s29, 0
	s_add_u32 s14, s14, 0x5800000
	s_addc_u32 s15, s15, 0
	s_add_u32 s14, s14, s62
	s_addc_u32 s15, s15, 0
	s_add_u32 s14, s14, s63
	s_addc_u32 s15, s15, 0
	s_lshl_b32 s64, s60, 8
	s_mul_i32 s64, s64, 0x2c00
	s_add_u32 s16, s28, 0x2c00000
	s_addc_u32 s17, s29, 0
	s_add_u32 s16, s16, s64
	s_addc_u32 s17, s17, 0
	s_add_u32 s16, s16, s62
	s_addc_u32 s17, s17, 0
	s_add_u32 s16, s16, s63
	s_addc_u32 s17, s17, 0
	s_lshl_b32 s76, s61, 7
	s_lshl_b32 s77, s40, 5
	s_add_u32 s76, s76, s77
	s_lshl_b32 s76, s76, 13
	s_lshl_b32 s77, s60, 10
	s_lshl_b32 s3, s59, 8
	s_add_u32 s76, s76, s77
	s_add_u32 s76, s76, s3
	s_add_u32 s18, s28, 0x2ec00000
	s_addc_u32 s19, s29, 0
	s_add_u32 s18, s18, s76
	s_addc_u32 s19, s19, 0
	s_add_u32 s42, s18, 0x20000
	s_addc_u32 s43, s19, 0
	s_lshl_b32 s62, s44, 10
	s_mov_b64 s[12:13], s[14:15]
	s_add_u32 s11, s62, 0x0
	s_mov_b32 m0, s11
	s_add_u32 s11, s11, 0x2000
	global_load_lds_dwordx4 v68, s[12:13]
	s_add_u32 s12, s12, 0x2c000
	s_addc_u32 s13, s13, 0
	s_mov_b32 m0, s11
	s_add_u32 s11, s11, 0x2000
	global_load_lds_dwordx4 v68, s[12:13]
	s_add_u32 s12, s12, 0x2c000
	s_addc_u32 s13, s13, 0
	s_mov_b32 m0, s11
	s_add_u32 s11, s11, 0x2000
	global_load_lds_dwordx4 v68, s[12:13]
	s_add_u32 s12, s12, 0x2c000
	s_addc_u32 s13, s13, 0
	s_mov_b32 m0, s11
	s_add_u32 s11, s11, 0x2000
	global_load_lds_dwordx4 v68, s[12:13]
	s_add_u32 s12, s12, 0x2c000
	s_addc_u32 s13, s13, 0
	s_mov_b32 m0, s11
	s_add_u32 s11, s11, 0x2000
	global_load_lds_dwordx4 v68, s[12:13]
	s_add_u32 s12, s12, 0x2c000
	s_addc_u32 s13, s13, 0
	s_mov_b32 m0, s11
	s_add_u32 s11, s11, 0x2000
	global_load_lds_dwordx4 v68, s[12:13]
	s_add_u32 s12, s12, 0x2c000
	s_addc_u32 s13, s13, 0
	s_mov_b32 m0, s11
	s_add_u32 s11, s11, 0x2000
	global_load_lds_dwordx4 v68, s[12:13]
	s_add_u32 s12, s12, 0x2c000
	s_addc_u32 s13, s13, 0
	s_mov_b32 m0, s11
	s_add_u32 s11, s11, 0x2000
	global_load_lds_dwordx4 v68, s[12:13]
	s_add_u32 s12, s12, 0x2c000
	s_addc_u32 s13, s13, 0
	s_mov_b64 s[12:13], s[16:17]
	s_add_u32 s11, s62, 0x10000
	s_mov_b32 m0, s11
	s_add_u32 s11, s11, 0x2000
	global_load_lds_dwordx4 v68, s[12:13]
	s_add_u32 s12, s12, 0x2c000
	s_addc_u32 s13, s13, 0
	s_mov_b32 m0, s11
	s_add_u32 s11, s11, 0x2000
	global_load_lds_dwordx4 v68, s[12:13]
	s_add_u32 s12, s12, 0x2c000
	s_addc_u32 s13, s13, 0
	s_mov_b32 m0, s11
	s_add_u32 s11, s11, 0x2000
	global_load_lds_dwordx4 v68, s[12:13]
	s_add_u32 s12, s12, 0x2c000
	s_addc_u32 s13, s13, 0
	s_mov_b32 m0, s11
	s_add_u32 s11, s11, 0x2000
	global_load_lds_dwordx4 v68, s[12:13]
	s_add_u32 s12, s12, 0x2c000
	s_addc_u32 s13, s13, 0
	s_mov_b32 m0, s11
	s_add_u32 s11, s11, 0x2000
	global_load_lds_dwordx4 v68, s[12:13]
	s_add_u32 s12, s12, 0x2c000
	s_addc_u32 s13, s13, 0
	s_mov_b32 m0, s11
	s_add_u32 s11, s11, 0x2000
	global_load_lds_dwordx4 v68, s[12:13]
	s_add_u32 s12, s12, 0x2c000
	s_addc_u32 s13, s13, 0
	s_mov_b32 m0, s11
	s_add_u32 s11, s11, 0x2000
	global_load_lds_dwordx4 v68, s[12:13]
	s_add_u32 s12, s12, 0x2c000
	s_addc_u32 s13, s13, 0
	s_mov_b32 m0, s11
	s_add_u32 s11, s11, 0x2000
	global_load_lds_dwordx4 v68, s[12:13]
	s_add_u32 s12, s12, 0x2c000
	s_addc_u32 s13, s13, 0
	s_add_u32 s16, s16, 0x160000
	s_addc_u32 s17, s17, 0
	s_waitcnt vmcnt(0)
	s_barrier
	ds_read_b128 v[84:87], v70 offset:0
	ds_read_b128 v[88:91], v70 offset:8192
	ds_read_b128 v[92:95], v74 offset:0
	ds_read_b128 v[96:99], v74 offset:8192
	ds_read_b128 v[100:103], v74 offset:16384
	ds_read_b128 v[104:107], v74 offset:24576
	ds_read_b128 v[108:111], v71 offset:0
	ds_read_b128 v[112:115], v71 offset:8192
	ds_read_b128 v[116:119], v75 offset:0
	ds_read_b128 v[120:123], v75 offset:8192
	ds_read_b128 v[124:127], v75 offset:16384
	ds_read_b128 v[128:131], v75 offset:24576
	s_waitcnt lgkmcnt(6)
	v_mfma_f32_16x16x32_bf16 v[0:3], v[92:95], v[84:87], 0
	v_mfma_f32_16x16x32_bf16 v[4:7], v[96:99], v[84:87], 0
	v_mfma_f32_16x16x32_bf16 v[8:11], v[100:103], v[84:87], 0
	v_mfma_f32_16x16x32_bf16 v[12:15], v[104:107], v[84:87], 0
	v_mfma_f32_16x16x32_bf16 v[32:35], v[92:95], v[88:91], 0
	v_mfma_f32_16x16x32_bf16 v[36:39], v[96:99], v[88:91], 0
	v_mfma_f32_16x16x32_bf16 v[40:43], v[100:103], v[88:91], 0
	v_mfma_f32_16x16x32_bf16 v[44:47], v[104:107], v[88:91], 0
	ds_read_b128 v[84:87], v72 offset:0
	ds_read_b128 v[88:91], v72 offset:8192
	ds_read_b128 v[92:95], v76 offset:0
	ds_read_b128 v[96:99], v76 offset:8192
	ds_read_b128 v[100:103], v76 offset:16384
	ds_read_b128 v[104:107], v76 offset:24576
	s_waitcnt lgkmcnt(6)
	v_mfma_f32_16x16x32_bf16 v[0:3], v[116:119], v[108:111], v[0:3]
	v_mfma_f32_16x16x32_bf16 v[4:7], v[120:123], v[108:111], v[4:7]
	v_mfma_f32_16x16x32_bf16 v[8:11], v[124:127], v[108:111], v[8:11]
	v_mfma_f32_16x16x32_bf16 v[12:15], v[128:131], v[108:111], v[12:15]
	v_mfma_f32_16x16x32_bf16 v[32:35], v[116:119], v[112:115], v[32:35]
	v_mfma_f32_16x16x32_bf16 v[36:39], v[120:123], v[112:115], v[36:39]
	v_mfma_f32_16x16x32_bf16 v[40:43], v[124:127], v[112:115], v[40:43]
	v_mfma_f32_16x16x32_bf16 v[44:47], v[128:131], v[112:115], v[44:47]
	ds_read_b128 v[108:111], v73 offset:0
	ds_read_b128 v[112:115], v73 offset:8192
	ds_read_b128 v[116:119], v77 offset:0
	ds_read_b128 v[120:123], v77 offset:8192
	ds_read_b128 v[124:127], v77 offset:16384
	ds_read_b128 v[128:131], v77 offset:24576
	s_waitcnt lgkmcnt(6)
	v_mfma_f32_16x16x32_bf16 v[0:3], v[92:95], v[84:87], v[0:3]
	v_mfma_f32_16x16x32_bf16 v[4:7], v[96:99], v[84:87], v[4:7]
	v_mfma_f32_16x16x32_bf16 v[8:11], v[100:103], v[84:87], v[8:11]
	v_mfma_f32_16x16x32_bf16 v[12:15], v[104:107], v[84:87], v[12:15]
	v_mfma_f32_16x16x32_bf16 v[32:35], v[92:95], v[88:91], v[32:35]
	v_mfma_f32_16x16x32_bf16 v[36:39], v[96:99], v[88:91], v[36:39]
	v_mfma_f32_16x16x32_bf16 v[40:43], v[100:103], v[88:91], v[40:43]
	v_mfma_f32_16x16x32_bf16 v[44:47], v[104:107], v[88:91], v[44:47]
	ds_read_b128 v[84:87], v70 offset:256
	ds_read_b128 v[88:91], v70 offset:8448
	ds_read_b128 v[92:95], v74 offset:256
	ds_read_b128 v[96:99], v74 offset:8448
	ds_read_b128 v[100:103], v74 offset:16640
	ds_read_b128 v[104:107], v74 offset:24832
	s_waitcnt lgkmcnt(6)
	v_mfma_f32_16x16x32_bf16 v[0:3], v[116:119], v[108:111], v[0:3]
	v_mfma_f32_16x16x32_bf16 v[4:7], v[120:123], v[108:111], v[4:7]
	v_mfma_f32_16x16x32_bf16 v[8:11], v[124:127], v[108:111], v[8:11]
	v_mfma_f32_16x16x32_bf16 v[12:15], v[128:131], v[108:111], v[12:15]
	v_mfma_f32_16x16x32_bf16 v[32:35], v[116:119], v[112:115], v[32:35]
	v_mfma_f32_16x16x32_bf16 v[36:39], v[120:123], v[112:115], v[36:39]
	v_mfma_f32_16x16x32_bf16 v[40:43], v[124:127], v[112:115], v[40:43]
	v_mfma_f32_16x16x32_bf16 v[44:47], v[128:131], v[112:115], v[44:47]
	ds_read_b128 v[108:111], v71 offset:256
	ds_read_b128 v[112:115], v71 offset:8448
	ds_read_b128 v[116:119], v75 offset:256
	ds_read_b128 v[120:123], v75 offset:8448
	ds_read_b128 v[124:127], v75 offset:16640
	ds_read_b128 v[128:131], v75 offset:24832
	s_waitcnt lgkmcnt(6)
	v_mfma_f32_16x16x32_bf16 v[0:3], v[92:95], v[84:87], v[0:3]
	v_mfma_f32_16x16x32_bf16 v[4:7], v[96:99], v[84:87], v[4:7]
	v_mfma_f32_16x16x32_bf16 v[8:11], v[100:103], v[84:87], v[8:11]
	v_mfma_f32_16x16x32_bf16 v[12:15], v[104:107], v[84:87], v[12:15]
	v_mfma_f32_16x16x32_bf16 v[32:35], v[92:95], v[88:91], v[32:35]
	v_mfma_f32_16x16x32_bf16 v[36:39], v[96:99], v[88:91], v[36:39]
	v_mfma_f32_16x16x32_bf16 v[40:43], v[100:103], v[88:91], v[40:43]
	v_mfma_f32_16x16x32_bf16 v[44:47], v[104:107], v[88:91], v[44:47]
	ds_read_b128 v[84:87], v72 offset:256
	ds_read_b128 v[88:91], v72 offset:8448
	ds_read_b128 v[92:95], v76 offset:256
	ds_read_b128 v[96:99], v76 offset:8448
	ds_read_b128 v[100:103], v76 offset:16640
	ds_read_b128 v[104:107], v76 offset:24832
	s_waitcnt lgkmcnt(6)
	v_mfma_f32_16x16x32_bf16 v[0:3], v[116:119], v[108:111], v[0:3]
	v_mfma_f32_16x16x32_bf16 v[4:7], v[120:123], v[108:111], v[4:7]
	v_mfma_f32_16x16x32_bf16 v[8:11], v[124:127], v[108:111], v[8:11]
	v_mfma_f32_16x16x32_bf16 v[12:15], v[128:131], v[108:111], v[12:15]
	v_mfma_f32_16x16x32_bf16 v[32:35], v[116:119], v[112:115], v[32:35]
	v_mfma_f32_16x16x32_bf16 v[36:39], v[120:123], v[112:115], v[36:39]
	v_mfma_f32_16x16x32_bf16 v[40:43], v[124:127], v[112:115], v[40:43]
	v_mfma_f32_16x16x32_bf16 v[44:47], v[128:131], v[112:115], v[44:47]
	ds_read_b128 v[108:111], v73 offset:256
	ds_read_b128 v[112:115], v73 offset:8448
	ds_read_b128 v[116:119], v77 offset:256
	ds_read_b128 v[120:123], v77 offset:8448
	ds_read_b128 v[124:127], v77 offset:16640
	ds_read_b128 v[128:131], v77 offset:24832
	s_waitcnt lgkmcnt(6)
	v_mfma_f32_16x16x32_bf16 v[0:3], v[92:95], v[84:87], v[0:3]
	v_mfma_f32_16x16x32_bf16 v[4:7], v[96:99], v[84:87], v[4:7]
	v_mfma_f32_16x16x32_bf16 v[8:11], v[100:103], v[84:87], v[8:11]
	v_mfma_f32_16x16x32_bf16 v[12:15], v[104:107], v[84:87], v[12:15]
	v_mfma_f32_16x16x32_bf16 v[32:35], v[92:95], v[88:91], v[32:35]
	v_mfma_f32_16x16x32_bf16 v[36:39], v[96:99], v[88:91], v[36:39]
	v_mfma_f32_16x16x32_bf16 v[40:43], v[100:103], v[88:91], v[40:43]
	v_mfma_f32_16x16x32_bf16 v[44:47], v[104:107], v[88:91], v[44:47]
	s_waitcnt lgkmcnt(0)
	v_mfma_f32_16x16x32_bf16 v[0:3], v[116:119], v[108:111], v[0:3]
	v_mfma_f32_16x16x32_bf16 v[4:7], v[120:123], v[108:111], v[4:7]
	v_mfma_f32_16x16x32_bf16 v[8:11], v[124:127], v[108:111], v[8:11]
	v_mfma_f32_16x16x32_bf16 v[12:15], v[128:131], v[108:111], v[12:15]
	v_mfma_f32_16x16x32_bf16 v[32:35], v[116:119], v[112:115], v[32:35]
	v_mfma_f32_16x16x32_bf16 v[36:39], v[120:123], v[112:115], v[36:39]
	v_mfma_f32_16x16x32_bf16 v[40:43], v[124:127], v[112:115], v[40:43]
	v_mfma_f32_16x16x32_bf16 v[44:47], v[128:131], v[112:115], v[44:47]
	s_barrier
	s_mov_b64 s[12:13], s[16:17]
	s_add_u32 s11, s62, 0x10000
	s_mov_b32 m0, s11
	s_add_u32 s11, s11, 0x2000
	global_load_lds_dwordx4 v68, s[12:13]
	s_add_u32 s12, s12, 0x2c000
	s_addc_u32 s13, s13, 0
	s_mov_b32 m0, s11
	s_add_u32 s11, s11, 0x2000
	global_load_lds_dwordx4 v68, s[12:13]
	s_add_u32 s12, s12, 0x2c000
	s_addc_u32 s13, s13, 0
	s_mov_b32 m0, s11
	s_add_u32 s11, s11, 0x2000
	global_load_lds_dwordx4 v68, s[12:13]
	s_add_u32 s12, s12, 0x2c000
	s_addc_u32 s13, s13, 0
	s_mov_b32 m0, s11
	s_add_u32 s11, s11, 0x2000
	global_load_lds_dwordx4 v68, s[12:13]
	s_add_u32 s12, s12, 0x2c000
	s_addc_u32 s13, s13, 0
	s_mov_b32 m0, s11
	s_add_u32 s11, s11, 0x2000
	global_load_lds_dwordx4 v68, s[12:13]
	s_add_u32 s12, s12, 0x2c000
	s_addc_u32 s13, s13, 0
	s_mov_b32 m0, s11
	s_add_u32 s11, s11, 0x2000
	global_load_lds_dwordx4 v68, s[12:13]
	s_add_u32 s12, s12, 0x2c000
	s_addc_u32 s13, s13, 0
	s_mov_b32 m0, s11
	s_add_u32 s11, s11, 0x2000
	global_load_lds_dwordx4 v68, s[12:13]
	s_add_u32 s12, s12, 0x2c000
	s_addc_u32 s13, s13, 0
	s_mov_b32 m0, s11
	s_add_u32 s11, s11, 0x2000
	global_load_lds_dwordx4 v68, s[12:13]
	s_add_u32 s12, s12, 0x2c000
	s_addc_u32 s13, s13, 0
	s_waitcnt vmcnt(0)
	s_barrier
	ds_read_b128 v[84:87], v70 offset:0
	ds_read_b128 v[88:91], v70 offset:8192
	ds_read_b128 v[92:95], v74 offset:0
	ds_read_b128 v[96:99], v74 offset:8192
	ds_read_b128 v[100:103], v74 offset:16384
	ds_read_b128 v[104:107], v74 offset:24576
	ds_read_b128 v[108:111], v71 offset:0
	ds_read_b128 v[112:115], v71 offset:8192
	ds_read_b128 v[116:119], v75 offset:0
	ds_read_b128 v[120:123], v75 offset:8192
	ds_read_b128 v[124:127], v75 offset:16384
	ds_read_b128 v[128:131], v75 offset:24576
	s_waitcnt lgkmcnt(6)
	v_mfma_f32_16x16x32_bf16 v[16:19], v[92:95], v[84:87], 0
	v_mfma_f32_16x16x32_bf16 v[20:23], v[96:99], v[84:87], 0
	v_mfma_f32_16x16x32_bf16 v[24:27], v[100:103], v[84:87], 0
	v_mfma_f32_16x16x32_bf16 v[28:31], v[104:107], v[84:87], 0
	v_mfma_f32_16x16x32_bf16 v[48:51], v[92:95], v[88:91], 0
	v_mfma_f32_16x16x32_bf16 v[52:55], v[96:99], v[88:91], 0
	v_mfma_f32_16x16x32_bf16 v[56:59], v[100:103], v[88:91], 0
	v_mfma_f32_16x16x32_bf16 v[60:63], v[104:107], v[88:91], 0
	ds_read_b128 v[84:87], v72 offset:0
	ds_read_b128 v[88:91], v72 offset:8192
	ds_read_b128 v[92:95], v76 offset:0
	ds_read_b128 v[96:99], v76 offset:8192
	ds_read_b128 v[100:103], v76 offset:16384
	ds_read_b128 v[104:107], v76 offset:24576
	s_waitcnt lgkmcnt(6)
	v_mfma_f32_16x16x32_bf16 v[16:19], v[116:119], v[108:111], v[16:19]
	v_mfma_f32_16x16x32_bf16 v[20:23], v[120:123], v[108:111], v[20:23]
	v_mfma_f32_16x16x32_bf16 v[24:27], v[124:127], v[108:111], v[24:27]
	v_mfma_f32_16x16x32_bf16 v[28:31], v[128:131], v[108:111], v[28:31]
	v_mfma_f32_16x16x32_bf16 v[48:51], v[116:119], v[112:115], v[48:51]
	v_mfma_f32_16x16x32_bf16 v[52:55], v[120:123], v[112:115], v[52:55]
	v_mfma_f32_16x16x32_bf16 v[56:59], v[124:127], v[112:115], v[56:59]
	v_mfma_f32_16x16x32_bf16 v[60:63], v[128:131], v[112:115], v[60:63]
	ds_read_b128 v[108:111], v73 offset:0
	ds_read_b128 v[112:115], v73 offset:8192
	ds_read_b128 v[116:119], v77 offset:0
	ds_read_b128 v[120:123], v77 offset:8192
	ds_read_b128 v[124:127], v77 offset:16384
	ds_read_b128 v[128:131], v77 offset:24576
	s_waitcnt lgkmcnt(6)
	v_mfma_f32_16x16x32_bf16 v[16:19], v[92:95], v[84:87], v[16:19]
	v_mfma_f32_16x16x32_bf16 v[20:23], v[96:99], v[84:87], v[20:23]
	v_mfma_f32_16x16x32_bf16 v[24:27], v[100:103], v[84:87], v[24:27]
	v_mfma_f32_16x16x32_bf16 v[28:31], v[104:107], v[84:87], v[28:31]
	v_mfma_f32_16x16x32_bf16 v[48:51], v[92:95], v[88:91], v[48:51]
	v_mfma_f32_16x16x32_bf16 v[52:55], v[96:99], v[88:91], v[52:55]
	v_mfma_f32_16x16x32_bf16 v[56:59], v[100:103], v[88:91], v[56:59]
	v_mfma_f32_16x16x32_bf16 v[60:63], v[104:107], v[88:91], v[60:63]
	ds_read_b128 v[84:87], v70 offset:256
	ds_read_b128 v[88:91], v70 offset:8448
	ds_read_b128 v[92:95], v74 offset:256
	ds_read_b128 v[96:99], v74 offset:8448
	ds_read_b128 v[100:103], v74 offset:16640
	ds_read_b128 v[104:107], v74 offset:24832
	s_waitcnt lgkmcnt(6)
	v_mfma_f32_16x16x32_bf16 v[16:19], v[116:119], v[108:111], v[16:19]
	v_mfma_f32_16x16x32_bf16 v[20:23], v[120:123], v[108:111], v[20:23]
	v_mfma_f32_16x16x32_bf16 v[24:27], v[124:127], v[108:111], v[24:27]
	v_mfma_f32_16x16x32_bf16 v[28:31], v[128:131], v[108:111], v[28:31]
	v_mfma_f32_16x16x32_bf16 v[48:51], v[116:119], v[112:115], v[48:51]
	v_mfma_f32_16x16x32_bf16 v[52:55], v[120:123], v[112:115], v[52:55]
	v_mfma_f32_16x16x32_bf16 v[56:59], v[124:127], v[112:115], v[56:59]
	v_mfma_f32_16x16x32_bf16 v[60:63], v[128:131], v[112:115], v[60:63]
	ds_read_b128 v[108:111], v71 offset:256
	ds_read_b128 v[112:115], v71 offset:8448
	ds_read_b128 v[116:119], v75 offset:256
	ds_read_b128 v[120:123], v75 offset:8448
	ds_read_b128 v[124:127], v75 offset:16640
	ds_read_b128 v[128:131], v75 offset:24832
	s_waitcnt lgkmcnt(6)
	v_mfma_f32_16x16x32_bf16 v[16:19], v[92:95], v[84:87], v[16:19]
	v_mfma_f32_16x16x32_bf16 v[20:23], v[96:99], v[84:87], v[20:23]
	v_mfma_f32_16x16x32_bf16 v[24:27], v[100:103], v[84:87], v[24:27]
	v_mfma_f32_16x16x32_bf16 v[28:31], v[104:107], v[84:87], v[28:31]
	v_mfma_f32_16x16x32_bf16 v[48:51], v[92:95], v[88:91], v[48:51]
	v_mfma_f32_16x16x32_bf16 v[52:55], v[96:99], v[88:91], v[52:55]
	v_mfma_f32_16x16x32_bf16 v[56:59], v[100:103], v[88:91], v[56:59]
	v_mfma_f32_16x16x32_bf16 v[60:63], v[104:107], v[88:91], v[60:63]
	ds_read_b128 v[84:87], v72 offset:256
	ds_read_b128 v[88:91], v72 offset:8448
	ds_read_b128 v[92:95], v76 offset:256
	ds_read_b128 v[96:99], v76 offset:8448
	ds_read_b128 v[100:103], v76 offset:16640
	ds_read_b128 v[104:107], v76 offset:24832
	s_waitcnt lgkmcnt(6)
	v_mfma_f32_16x16x32_bf16 v[16:19], v[116:119], v[108:111], v[16:19]
	v_mfma_f32_16x16x32_bf16 v[20:23], v[120:123], v[108:111], v[20:23]
	v_mfma_f32_16x16x32_bf16 v[24:27], v[124:127], v[108:111], v[24:27]
	v_mfma_f32_16x16x32_bf16 v[28:31], v[128:131], v[108:111], v[28:31]
	v_mfma_f32_16x16x32_bf16 v[48:51], v[116:119], v[112:115], v[48:51]
	v_mfma_f32_16x16x32_bf16 v[52:55], v[120:123], v[112:115], v[52:55]
	v_mfma_f32_16x16x32_bf16 v[56:59], v[124:127], v[112:115], v[56:59]
	v_mfma_f32_16x16x32_bf16 v[60:63], v[128:131], v[112:115], v[60:63]
	ds_read_b128 v[108:111], v73 offset:256
	ds_read_b128 v[112:115], v73 offset:8448
	ds_read_b128 v[116:119], v77 offset:256
	ds_read_b128 v[120:123], v77 offset:8448
	ds_read_b128 v[124:127], v77 offset:16640
	ds_read_b128 v[128:131], v77 offset:24832
	s_waitcnt lgkmcnt(6)
	v_mfma_f32_16x16x32_bf16 v[16:19], v[92:95], v[84:87], v[16:19]
	v_mfma_f32_16x16x32_bf16 v[20:23], v[96:99], v[84:87], v[20:23]
	v_mfma_f32_16x16x32_bf16 v[24:27], v[100:103], v[84:87], v[24:27]
	v_mfma_f32_16x16x32_bf16 v[28:31], v[104:107], v[84:87], v[28:31]
	v_mfma_f32_16x16x32_bf16 v[48:51], v[92:95], v[88:91], v[48:51]
	v_mfma_f32_16x16x32_bf16 v[52:55], v[96:99], v[88:91], v[52:55]
	v_mfma_f32_16x16x32_bf16 v[56:59], v[100:103], v[88:91], v[56:59]
	v_mfma_f32_16x16x32_bf16 v[60:63], v[104:107], v[88:91], v[60:63]
	s_waitcnt lgkmcnt(0)
	v_mfma_f32_16x16x32_bf16 v[16:19], v[116:119], v[108:111], v[16:19]
	v_mfma_f32_16x16x32_bf16 v[20:23], v[120:123], v[108:111], v[20:23]
	v_mfma_f32_16x16x32_bf16 v[24:27], v[124:127], v[108:111], v[24:27]
	v_mfma_f32_16x16x32_bf16 v[28:31], v[128:131], v[108:111], v[28:31]
	v_mfma_f32_16x16x32_bf16 v[48:51], v[116:119], v[112:115], v[48:51]
	v_mfma_f32_16x16x32_bf16 v[52:55], v[120:123], v[112:115], v[52:55]
	v_mfma_f32_16x16x32_bf16 v[56:59], v[124:127], v[112:115], v[56:59]
	v_mfma_f32_16x16x32_bf16 v[60:63], v[128:131], v[112:115], v[60:63]
	s_nop 7
	global_store_dwordx4 v69, v[0:3], s[18:19] offset:0
	global_store_dwordx4 v69, v[4:7], s[18:19] offset:64
	global_store_dwordx4 v69, v[8:11], s[18:19] offset:128
	global_store_dwordx4 v69, v[12:15], s[18:19] offset:192
	global_store_dwordx4 v69, v[16:19], s[18:19] offset:512
	global_store_dwordx4 v69, v[20:23], s[18:19] offset:576
	global_store_dwordx4 v69, v[24:27], s[18:19] offset:640
	global_store_dwordx4 v69, v[28:31], s[18:19] offset:704
	global_store_dwordx4 v69, v[32:35], s[42:43] offset:0
	global_store_dwordx4 v69, v[36:39], s[42:43] offset:64
	global_store_dwordx4 v69, v[40:43], s[42:43] offset:128
	global_store_dwordx4 v69, v[44:47], s[42:43] offset:192
	global_store_dwordx4 v69, v[48:51], s[42:43] offset:512
	global_store_dwordx4 v69, v[52:55], s[42:43] offset:576
	global_store_dwordx4 v69, v[56:59], s[42:43] offset:640
	global_store_dwordx4 v69, v[60:63], s[42:43] offset:704
	s_barrier
.Lmain_2:
	v_lshlrev_b32_e32 v0, 4, v231
	v_bitop3_b32 v8, v0, v239, 48 bitop3:0x6c
	s_movk_i32 s6, 0x70
	v_or_b32_e32 v1, v8, v139
	v_and_b32_e32 v2, 4, v237
	v_and_b32_e32 v150, 24, v238
	v_and_or_b32 v3, v236, s6, v234
	v_lshrrev_b32_e32 v1, 1, v1
	v_or3_b32 v2, v2, v235, v150
	s_movk_i32 s6, 0x60
	v_mul_u32_u24_e32 v9, 0x1600, v3
	v_and_or_b32 v4, v236, s6, v2
	v_or_b32_e32 v3, v1, v9
	v_lshlrev_b32_e32 v128, 1, v3
	v_mul_u32_u24_e32 v3, 0x1600, v4
	v_add_u32_e32 v0, 0x2000, v0
	v_or_b32_e32 v3, v3, v1
	v_lshrrev_b32_e32 v0, 7, v0
	s_movk_i32 s6, 0xf0
	v_lshlrev_b32_e32 v130, 1, v3
	v_and_or_b32 v3, v0, s6, v234
	s_movk_i32 s6, 0xe0
	v_and_or_b32 v0, v0, s6, v2
	v_mul_u32_u24_e32 v0, 0x1600, v0
	s_add_u32 s3, s28, 0x2c00000
	v_mul_u32_u24_e32 v10, 0x1600, v3
	v_or_b32_e32 v0, v0, v1
	s_addc_u32 s62, s29, 0
	v_or_b32_e32 v2, v10, v1
	v_lshlrev_b32_e32 v134, 1, v0
	v_lshlrev_b32_e32 v152, 1, v150
	v_and_b32_e32 v0, 0x3c0, v233
	v_and_b32_e32 v1, 32, v138
	s_ashr_i32 s63, s34, 31
	s_ashr_i32 s64, s2, 31
	v_mov_b32_e32 v131, 0
	v_lshlrev_b32_e32 v132, 1, v2
	v_bitop3_b32 v151, v152, v1, v0 bitop3:0x36
	s_cmpk_gt_i32 s2, 0xff
	v_mov_b32_e32 v135, v131
	v_mov_b32_e32 v129, v131
	v_mov_b32_e32 v133, v131
	v_readfirstlane_b32 s6, v231
	s_cbranch_scc1 .LBB0_342
	s_lshr_b32 s10, s64, 29
	s_add_i32 s10, s2, s10
	s_and_b32 s11, s10, -8
	s_lshr_b32 s12, s6, 6
	s_sub_i32 s11, s2, s11
	s_lshr_b32 s7, s6, 8
	s_lshl_b32 s17, s12, 10
	s_lshl_b32 s14, s11, 5
	s_ashr_i32 s10, s10, 3
	s_mul_i32 s13, s11, 33
	s_cmp_lt_i32 s11, 0
	s_cselect_b32 s11, s13, s14
	s_add_i32 s10, s11, s10
	s_ashr_i32 s11, s10, 31
	s_lshr_b32 s11, s11, 26
	s_add_i32 s11, s10, s11
	s_ashr_i32 s13, s11, 6
	s_andn2_b32 s11, s11, 63
	s_sub_i32 s10, s10, s11
	s_bfe_i32 s11, s10, 0x80000
	s_bfe_u32 s11, s11, 0x3000c
	s_add_i32 s11, s10, s11
	s_lshl_b32 s14, s13, 3
	s_bfe_i32 s13, s11, 0x80000
	s_and_b32 s11, s11, 0xf8
	s_sub_i32 s10, s10, s11
	s_sext_i32_i8 s10, s10
	s_sext_i32_i16 s15, s13
	s_add_i32 s14, s14, s10
	s_lshr_b32 s13, s15, 3
	s_mul_i32 s11, s14, 0x2c0000
	s_mul_hi_i32 s10, s14, 0x2c0000
	s_add_u32 s22, s52, s11
	s_addc_u32 s23, s53, s10
	s_ashr_i32 s10, s15, 3
	s_mul_hi_i32 s11, s10, 0x2c0000
	s_mul_i32 s10, s10, 0x2c0000
	s_add_u32 s24, s3, s10
	s_addc_u32 s25, s62, s11
	s_add_i32 s36, s17, 0
	s_add_i32 m0, s36, 0x10000
	v_lshl_add_u64 v[0:1], s[24:25], 0, v[130:131]
	global_load_lds_dwordx4 v[0:1], off
	s_add_i32 m0, s36, 0x12000
	s_add_u32 s10, s24, 0x160000
	v_lshl_add_u64 v[2:3], s[24:25], 0, v[134:135]
	s_addc_u32 s11, s25, 0
	global_load_lds_dwordx4 v[2:3], off
	s_add_i32 m0, s36, 0x14000
	v_lshl_add_u64 v[4:5], s[10:11], 0, v[130:131]
	global_load_lds_dwordx4 v[4:5], off
	v_lshl_add_u64 v[4:5], s[10:11], 0, v[134:135]
	s_add_i32 m0, s36, 0x16000
	s_add_i32 s37, s36, 0x2000
	global_load_lds_dwordx4 v[4:5], off
	v_lshl_add_u64 v[6:7], s[22:23], 0, v[128:129]
	s_mov_b32 m0, s36
	s_add_u32 s10, s22, 0x160000
	global_load_lds_dwordx4 v[6:7], off
	v_lshl_add_u64 v[4:5], s[22:23], 0, v[132:133]
	s_mov_b32 m0, s37
	s_addc_u32 s11, s23, 0
	s_add_i32 s38, s36, 0x4000
	global_load_lds_dwordx4 v[4:5], off
	v_lshl_add_u64 v[12:13], s[10:11], 0, v[128:129]
	s_mov_b32 m0, s38
	s_add_i32 s39, s36, 0x6000
	global_load_lds_dwordx4 v[12:13], off
	v_lshl_add_u64 v[12:13], s[10:11], 0, v[132:133]
	s_mov_b32 m0, s39
	s_cmp_eq_u32 s7, 1
	global_load_lds_dwordx4 v[12:13], off
	s_cselect_b64 s[10:11], -1, 0
	s_cmp_lg_u32 s7, 1
	s_mov_b32 s40, 0
	s_cbranch_scc1 .LBB0_325
	s_barrier

.LBB0_342:
	s_cmpk_gt_i32 s2, 0xaf
	v_readfirstlane_b32 s7, v231
.LBB0_358:
	s_cmp_gt_i32 s31, 3
	s_cselect_b64 s[6:7], -1, 0
	s_and_b64 s[8:9], s[8:9], s[6:7]
	s_andn2_b64 vcc, exec, s[8:9]
	s_cbranch_vccnz .LBB0_412
	s_waitcnt vmcnt(0)
	s_waitcnt vmcnt(0) lgkmcnt(0)
	s_barrier
	s_and_saveexec_b64 s[8:9], s[4:5]
	s_cbranch_execz .LBB0_411
	s_add_i32 s3, 0, 0x20000
	v_mov_b32_e32 v0, s3
	s_waitcnt vmcnt(0) expcnt(0) lgkmcnt(0)
	ds_read_b32 v2, v0
	s_add_i32 s3, 0, 0x20004
	v_mov_b32_e32 v0, s3
	ds_read_b32 v0, v0
	s_waitcnt lgkmcnt(1)
	v_cmp_ne_u32_e32 vcc, 0, v2
	s_cbranch_vccnz .LBB0_375
	s_add_u32 s10, s28, 0x30300200
	s_addc_u32 s11, s29, 0
	s_add_u32 s12, s28, 0x30300400
	s_addc_u32 s13, s29, 0
	s_add_u32 s14, s28, 0x30300500
	s_addc_u32 s15, s29, 0
	s_add_u32 s16, s28, 0x30300600
	s_addc_u32 s17, s29, 0
	s_add_u32 s18, s28, 0x30300700
	s_addc_u32 s19, s29, 0
	s_add_u32 s20, s28, 0x30300800
	s_addc_u32 s21, s29, 0
	s_add_u32 s22, s28, 0x30300900
	s_addc_u32 s23, s29, 0
	s_add_u32 s24, s28, 0x30300a00
	s_addc_u32 s25, s29, 0
	s_add_u32 s26, s28, 0x30300b00
	s_addc_u32 s27, s29, 0
	s_add_u32 s36, s28, 0x30300c00
	s_addc_u32 s37, s29, 0
	s_add_u32 s38, s28, 0x30300d00
	s_addc_u32 s39, s29, 0
	s_add_u32 s40, s28, 0x30300e00
	s_addc_u32 s41, s29, 0
	s_add_u32 s42, s28, 0x30300f00
	s_addc_u32 s43, s29, 0
	s_add_u32 s44, s28, 0x30301000
	s_addc_u32 s45, s29, 0
	s_add_u32 s46, s28, 0x30301100
	s_addc_u32 s47, s29, 0
	s_add_u32 s58, s28, 0x30301200
	s_addc_u32 s59, s29, 0
	s_mul_i32 s3, s35, s82
	s_add_u32 s60, s28, 0x30301300
	s_mul_i32 s3, s3, s34
	s_addc_u32 s61, s29, 0
	s_mov_b32 s68, 1
	v_mov_b32_e32 v16, 0
	s_branch .LBB0_363

.LBB0_1635:
	s_cmp_lt_i32 s30, 10
	s_cselect_b64 s[8:9], -1, 0
	s_and_b64 s[8:9], s[8:9], s[6:7]
	s_andn2_b64 vcc, exec, s[8:9]
	s_cbranch_vccnz .LBB0_1672
	s_cmp_gt_i32 s2, 63
	s_cbranch_scc1 .Lmain_9
	v_and_b32_e32 v64, 63, v231
	v_and_b32_e32 v65, 15, v64
	v_bfe_u32 v66, v64, 4, 2
	v_readfirstlane_b32 s44, v230
	s_and_b32 s60, s2, 7
	s_lshr_b32 s61, s2, 3
	s_lshl_b32 s63, s61, 9
	s_nop 0
	s_and_b32 s40, s44, 3
	s_lshr_b32 s59, s44, 2
	v_and_b32_e32 v67, 3, v65
	v_xor_b32_e32 v67, v66, v67
	v_lshlrev_b32_e32 v67, 4, v67
	v_lshl_add_u32 v67, v65, 9, v67
	v_lshrrev_b32_e32 v69, 2, v65
	s_lshl_b32 s64, s40, 14
	s_lshl_b32 s76, s59, 15
	s_add_u32 s76, s76, 0x10000
	v_xor_b32_e32 v70, 0, v69
	v_lshl_add_u32 v70, v70, 6, v67
	v_add_u32_e32 v74, s76, v70
	v_add_u32_e32 v70, s64, v70
	v_xor_b32_e32 v71, 1, v69
	v_lshl_add_u32 v71, v71, 6, v67
	v_add_u32_e32 v75, s76, v71
	v_add_u32_e32 v71, s64, v71
	v_xor_b32_e32 v72, 2, v69
	v_lshl_add_u32 v72, v72, 6, v67
	v_add_u32_e32 v76, s76, v72
	v_add_u32_e32 v72, s64, v72
	v_xor_b32_e32 v73, 3, v69
	v_lshl_add_u32 v73, v73, 6, v67
	v_add_u32_e32 v77, s76, v73
	v_add_u32_e32 v73, s64, v73
	v_lshrrev_b32_e32 v68, 5, v64
	s_lshl_b32 s77, s44, 1
	v_add_u32_e32 v69, s77, v68
	v_and_b32_e32 v67, 31, v64
	v_xor_b32_e32 v67, v67, v69
	v_lshlrev_b32_e32 v67, 4, v67
	v_mul_u32_u24_e32 v68, 0x1000, v68
	v_add_u32_e32 v68, v68, v67
	v_lshlrev_b32_e32 v69, 13, v65
	v_lshl_add_u32 v69, v66, 4, v69
	s_lshl_b32 s62, s44, 1
	s_mul_i32 s62, s62, 0x1000
	s_add_u32 s14, s28, 0x2bf00000
	s_addc_u32 s15, s29, 0
	s_add_u32 s14, s14, 0x2000000
	s_addc_u32 s15, s15, 0
	s_add_u32 s14, s14, s62
	s_addc_u32 s15, s15, 0
	s_add_u32 s14, s14, s63
	s_addc_u32 s15, s15, 0
	s_lshl_b32 s64, s60, 8
	s_mul_i32 s64, s64, 0x1000
	s_add_u32 s16, s28, 0x5800000
	s_addc_u32 s17, s29, 0
	s_add_u32 s16, s16, s64
	s_addc_u32 s17, s17, 0
	s_add_u32 s16, s16, s62
	s_addc_u32 s17, s17, 0
	s_add_u32 s16, s16, s63
	s_addc_u32 s17, s17, 0
	s_lshl_b32 s76, s61, 7
	s_lshl_b32 s77, s40, 5
	s_add_u32 s76, s76, s77
	s_lshl_b32 s76, s76, 13
	s_lshl_b32 s77, s60, 10
	s_lshl_b32 s3, s59, 8
	s_add_u32 s76, s76, s77
	s_add_u32 s76, s76, s3
	s_add_u32 s18, s28, 0x2ec00000
	s_addc_u32 s19, s29, 0
	s_add_u32 s18, s18, s76
	s_addc_u32 s19, s19, 0
	s_add_u32 s42, s18, 0x20000
	s_addc_u32 s43, s19, 0
	s_lshl_b32 s62, s44, 10
	s_mov_b64 s[12:13], s[14:15]
	s_add_u32 s11, s62, 0x0
	s_mov_b32 m0, s11
	s_add_u32 s11, s11, 0x2000
	global_load_lds_dwordx4 v68, s[12:13]
	s_add_u32 s12, s12, 0x10000
	s_addc_u32 s13, s13, 0
	s_mov_b32 m0, s11
	s_add_u32 s11, s11, 0x2000
	global_load_lds_dwordx4 v68, s[12:13]
	s_add_u32 s12, s12, 0x10000
	s_addc_u32 s13, s13, 0
	s_mov_b32 m0, s11
	s_add_u32 s11, s11, 0x2000
	global_load_lds_dwordx4 v68, s[12:13]
	s_add_u32 s12, s12, 0x10000
	s_addc_u32 s13, s13, 0
	s_mov_b32 m0, s11
	s_add_u32 s11, s11, 0x2000
	global_load_lds_dwordx4 v68, s[12:13]
	s_add_u32 s12, s12, 0x10000
	s_addc_u32 s13, s13, 0
	s_mov_b32 m0, s11
	s_add_u32 s11, s11, 0x2000
	global_load_lds_dwordx4 v68, s[12:13]
	s_add_u32 s12, s12, 0x10000
	s_addc_u32 s13, s13, 0
	s_mov_b32 m0, s11
	s_add_u32 s11, s11, 0x2000
	global_load_lds_dwordx4 v68, s[12:13]
	s_add_u32 s12, s12, 0x10000
	s_addc_u32 s13, s13, 0
	s_mov_b32 m0, s11
	s_add_u32 s11, s11, 0x2000
	global_load_lds_dwordx4 v68, s[12:13]
	s_add_u32 s12, s12, 0x10000
	s_addc_u32 s13, s13, 0
	s_mov_b32 m0, s11
	s_add_u32 s11, s11, 0x2000
	global_load_lds_dwordx4 v68, s[12:13]
	s_add_u32 s12, s12, 0x10000
	s_addc_u32 s13, s13, 0
	s_mov_b64 s[12:13], s[16:17]
	s_add_u32 s11, s62, 0x10000
	s_mov_b32 m0, s11
	s_add_u32 s11, s11, 0x2000
	global_load_lds_dwordx4 v68, s[12:13]
	s_add_u32 s12, s12, 0x10000
	s_addc_u32 s13, s13, 0
	s_mov_b32 m0, s11
	s_add_u32 s11, s11, 0x2000
	global_load_lds_dwordx4 v68, s[12:13]
	s_add_u32 s12, s12, 0x10000
	s_addc_u32 s13, s13, 0
	s_mov_b32 m0, s11
	s_add_u32 s11, s11, 0x2000
	global_load_lds_dwordx4 v68, s[12:13]
	s_add_u32 s12, s12, 0x10000
	s_addc_u32 s13, s13, 0
	s_mov_b32 m0, s11
	s_add_u32 s11, s11, 0x2000
	global_load_lds_dwordx4 v68, s[12:13]
	s_add_u32 s12, s12, 0x10000
	s_addc_u32 s13, s13, 0
	s_mov_b32 m0, s11
	s_add_u32 s11, s11, 0x2000
	global_load_lds_dwordx4 v68, s[12:13]
	s_add_u32 s12, s12, 0x10000
	s_addc_u32 s13, s13, 0
	s_mov_b32 m0, s11
	s_add_u32 s11, s11, 0x2000
	global_load_lds_dwordx4 v68, s[12:13]
	s_add_u32 s12, s12, 0x10000
	s_addc_u32 s13, s13, 0
	s_mov_b32 m0, s11
	s_add_u32 s11, s11, 0x2000
	global_load_lds_dwordx4 v68, s[12:13]
	s_add_u32 s12, s12, 0x10000
	s_addc_u32 s13, s13, 0
	s_mov_b32 m0, s11
	s_add_u32 s11, s11, 0x2000
	global_load_lds_dwordx4 v68, s[12:13]
	s_add_u32 s12, s12, 0x10000
	s_addc_u32 s13, s13, 0
	s_add_u32 s16, s16, 0x80000
	s_addc_u32 s17, s17, 0
	s_waitcnt vmcnt(0)
	s_barrier
	ds_read_b128 v[84:87], v70 offset:0
	ds_read_b128 v[88:91], v70 offset:8192
	ds_read_b128 v[92:95], v74 offset:0
	ds_read_b128 v[96:99], v74 offset:8192
	ds_read_b128 v[100:103], v74 offset:16384
	ds_read_b128 v[104:107], v74 offset:24576
	ds_read_b128 v[108:111], v71 offset:0
	ds_read_b128 v[112:115], v71 offset:8192
	ds_read_b128 v[116:119], v75 offset:0
	ds_read_b128 v[120:123], v75 offset:8192
	ds_read_b128 v[124:127], v75 offset:16384
	ds_read_b128 v[128:131], v75 offset:24576
	s_waitcnt lgkmcnt(6)
	v_mfma_f32_16x16x32_bf16 v[0:3], v[92:95], v[84:87], 0
	v_mfma_f32_16x16x32_bf16 v[4:7], v[96:99], v[84:87], 0
	v_mfma_f32_16x16x32_bf16 v[8:11], v[100:103], v[84:87], 0
	v_mfma_f32_16x16x32_bf16 v[12:15], v[104:107], v[84:87], 0
	v_mfma_f32_16x16x32_bf16 v[32:35], v[92:95], v[88:91], 0
	v_mfma_f32_16x16x32_bf16 v[36:39], v[96:99], v[88:91], 0
	v_mfma_f32_16x16x32_bf16 v[40:43], v[100:103], v[88:91], 0
	v_mfma_f32_16x16x32_bf16 v[44:47], v[104:107], v[88:91], 0
	ds_read_b128 v[84:87], v72 offset:0
	ds_read_b128 v[88:91], v72 offset:8192
	ds_read_b128 v[92:95], v76 offset:0
	ds_read_b128 v[96:99], v76 offset:8192
	ds_read_b128 v[100:103], v76 offset:16384
	ds_read_b128 v[104:107], v76 offset:24576
	s_waitcnt lgkmcnt(6)
	v_mfma_f32_16x16x32_bf16 v[0:3], v[116:119], v[108:111], v[0:3]
	v_mfma_f32_16x16x32_bf16 v[4:7], v[120:123], v[108:111], v[4:7]
	v_mfma_f32_16x16x32_bf16 v[8:11], v[124:127], v[108:111], v[8:11]
	v_mfma_f32_16x16x32_bf16 v[12:15], v[128:131], v[108:111], v[12:15]
	v_mfma_f32_16x16x32_bf16 v[32:35], v[116:119], v[112:115], v[32:35]
	v_mfma_f32_16x16x32_bf16 v[36:39], v[120:123], v[112:115], v[36:39]
	v_mfma_f32_16x16x32_bf16 v[40:43], v[124:127], v[112:115], v[40:43]
	v_mfma_f32_16x16x32_bf16 v[44:47], v[128:131], v[112:115], v[44:47]
	ds_read_b128 v[108:111], v73 offset:0
	ds_read_b128 v[112:115], v73 offset:8192
	ds_read_b128 v[116:119], v77 offset:0
	ds_read_b128 v[120:123], v77 offset:8192
	ds_read_b128 v[124:127], v77 offset:16384
	ds_read_b128 v[128:131], v77 offset:24576
	s_waitcnt lgkmcnt(6)
	v_mfma_f32_16x16x32_bf16 v[0:3], v[92:95], v[84:87], v[0:3]
	v_mfma_f32_16x16x32_bf16 v[4:7], v[96:99], v[84:87], v[4:7]
	v_mfma_f32_16x16x32_bf16 v[8:11], v[100:103], v[84:87], v[8:11]
	v_mfma_f32_16x16x32_bf16 v[12:15], v[104:107], v[84:87], v[12:15]
	v_mfma_f32_16x16x32_bf16 v[32:35], v[92:95], v[88:91], v[32:35]
	v_mfma_f32_16x16x32_bf16 v[36:39], v[96:99], v[88:91], v[36:39]
	v_mfma_f32_16x16x32_bf16 v[40:43], v[100:103], v[88:91], v[40:43]
	v_mfma_f32_16x16x32_bf16 v[44:47], v[104:107], v[88:91], v[44:47]
	ds_read_b128 v[84:87], v70 offset:256
	ds_read_b128 v[88:91], v70 offset:8448
	ds_read_b128 v[92:95], v74 offset:256
	ds_read_b128 v[96:99], v74 offset:8448
	ds_read_b128 v[100:103], v74 offset:16640
	ds_read_b128 v[104:107], v74 offset:24832
	s_waitcnt lgkmcnt(6)
	v_mfma_f32_16x16x32_bf16 v[0:3], v[116:119], v[108:111], v[0:3]
	v_mfma_f32_16x16x32_bf16 v[4:7], v[120:123], v[108:111], v[4:7]
	v_mfma_f32_16x16x32_bf16 v[8:11], v[124:127], v[108:111], v[8:11]
	v_mfma_f32_16x16x32_bf16 v[12:15], v[128:131], v[108:111], v[12:15]
	v_mfma_f32_16x16x32_bf16 v[32:35], v[116:119], v[112:115], v[32:35]
	v_mfma_f32_16x16x32_bf16 v[36:39], v[120:123], v[112:115], v[36:39]
	v_mfma_f32_16x16x32_bf16 v[40:43], v[124:127], v[112:115], v[40:43]
	v_mfma_f32_16x16x32_bf16 v[44:47], v[128:131], v[112:115], v[44:47]
	ds_read_b128 v[108:111], v71 offset:256
	ds_read_b128 v[112:115], v71 offset:8448
	ds_read_b128 v[116:119], v75 offset:256
	ds_read_b128 v[120:123], v75 offset:8448
	ds_read_b128 v[124:127], v75 offset:16640
	ds_read_b128 v[128:131], v75 offset:24832
	s_waitcnt lgkmcnt(6)
	v_mfma_f32_16x16x32_bf16 v[0:3], v[92:95], v[84:87], v[0:3]
	v_mfma_f32_16x16x32_bf16 v[4:7], v[96:99], v[84:87], v[4:7]
	v_mfma_f32_16x16x32_bf16 v[8:11], v[100:103], v[84:87], v[8:11]
	v_mfma_f32_16x16x32_bf16 v[12:15], v[104:107], v[84:87], v[12:15]
	v_mfma_f32_16x16x32_bf16 v[32:35], v[92:95], v[88:91], v[32:35]
	v_mfma_f32_16x16x32_bf16 v[36:39], v[96:99], v[88:91], v[36:39]
	v_mfma_f32_16x16x32_bf16 v[40:43], v[100:103], v[88:91], v[40:43]
	v_mfma_f32_16x16x32_bf16 v[44:47], v[104:107], v[88:91], v[44:47]
	ds_read_b128 v[84:87], v72 offset:256
	ds_read_b128 v[88:91], v72 offset:8448
	ds_read_b128 v[92:95], v76 offset:256
	ds_read_b128 v[96:99], v76 offset:8448
	ds_read_b128 v[100:103], v76 offset:16640
	ds_read_b128 v[104:107], v76 offset:24832
	s_waitcnt lgkmcnt(6)
	v_mfma_f32_16x16x32_bf16 v[0:3], v[116:119], v[108:111], v[0:3]
	v_mfma_f32_16x16x32_bf16 v[4:7], v[120:123], v[108:111], v[4:7]
	v_mfma_f32_16x16x32_bf16 v[8:11], v[124:127], v[108:111], v[8:11]
	v_mfma_f32_16x16x32_bf16 v[12:15], v[128:131], v[108:111], v[12:15]
	v_mfma_f32_16x16x32_bf16 v[32:35], v[116:119], v[112:115], v[32:35]
	v_mfma_f32_16x16x32_bf16 v[36:39], v[120:123], v[112:115], v[36:39]
	v_mfma_f32_16x16x32_bf16 v[40:43], v[124:127], v[112:115], v[40:43]
	v_mfma_f32_16x16x32_bf16 v[44:47], v[128:131], v[112:115], v[44:47]
	ds_read_b128 v[108:111], v73 offset:256
	ds_read_b128 v[112:115], v73 offset:8448
	ds_read_b128 v[116:119], v77 offset:256
	ds_read_b128 v[120:123], v77 offset:8448
	ds_read_b128 v[124:127], v77 offset:16640
	ds_read_b128 v[128:131], v77 offset:24832
	s_waitcnt lgkmcnt(6)
	v_mfma_f32_16x16x32_bf16 v[0:3], v[92:95], v[84:87], v[0:3]
	v_mfma_f32_16x16x32_bf16 v[4:7], v[96:99], v[84:87], v[4:7]
	v_mfma_f32_16x16x32_bf16 v[8:11], v[100:103], v[84:87], v[8:11]
	v_mfma_f32_16x16x32_bf16 v[12:15], v[104:107], v[84:87], v[12:15]
	v_mfma_f32_16x16x32_bf16 v[32:35], v[92:95], v[88:91], v[32:35]
	v_mfma_f32_16x16x32_bf16 v[36:39], v[96:99], v[88:91], v[36:39]
	v_mfma_f32_16x16x32_bf16 v[40:43], v[100:103], v[88:91], v[40:43]
	v_mfma_f32_16x16x32_bf16 v[44:47], v[104:107], v[88:91], v[44:47]
	s_waitcnt lgkmcnt(0)
	v_mfma_f32_16x16x32_bf16 v[0:3], v[116:119], v[108:111], v[0:3]
	v_mfma_f32_16x16x32_bf16 v[4:7], v[120:123], v[108:111], v[4:7]
	v_mfma_f32_16x16x32_bf16 v[8:11], v[124:127], v[108:111], v[8:11]
	v_mfma_f32_16x16x32_bf16 v[12:15], v[128:131], v[108:111], v[12:15]
	v_mfma_f32_16x16x32_bf16 v[32:35], v[116:119], v[112:115], v[32:35]
	v_mfma_f32_16x16x32_bf16 v[36:39], v[120:123], v[112:115], v[36:39]
	v_mfma_f32_16x16x32_bf16 v[40:43], v[124:127], v[112:115], v[40:43]
	v_mfma_f32_16x16x32_bf16 v[44:47], v[128:131], v[112:115], v[44:47]
	s_barrier
	s_mov_b64 s[12:13], s[16:17]
	s_add_u32 s11, s62, 0x10000
	s_mov_b32 m0, s11
	s_add_u32 s11, s11, 0x2000
	global_load_lds_dwordx4 v68, s[12:13]
	s_add_u32 s12, s12, 0x10000
	s_addc_u32 s13, s13, 0
	s_mov_b32 m0, s11
	s_add_u32 s11, s11, 0x2000
	global_load_lds_dwordx4 v68, s[12:13]
	s_add_u32 s12, s12, 0x10000
	s_addc_u32 s13, s13, 0
	s_mov_b32 m0, s11
	s_add_u32 s11, s11, 0x2000
	global_load_lds_dwordx4 v68, s[12:13]
	s_add_u32 s12, s12, 0x10000
	s_addc_u32 s13, s13, 0
	s_mov_b32 m0, s11
	s_add_u32 s11, s11, 0x2000
	global_load_lds_dwordx4 v68, s[12:13]
	s_add_u32 s12, s12, 0x10000
	s_addc_u32 s13, s13, 0
	s_mov_b32 m0, s11
	s_add_u32 s11, s11, 0x2000
	global_load_lds_dwordx4 v68, s[12:13]
	s_add_u32 s12, s12, 0x10000
	s_addc_u32 s13, s13, 0
	s_mov_b32 m0, s11
	s_add_u32 s11, s11, 0x2000
	global_load_lds_dwordx4 v68, s[12:13]
	s_add_u32 s12, s12, 0x10000
	s_addc_u32 s13, s13, 0
	s_mov_b32 m0, s11
	s_add_u32 s11, s11, 0x2000
	global_load_lds_dwordx4 v68, s[12:13]
	s_add_u32 s12, s12, 0x10000
	s_addc_u32 s13, s13, 0
	s_mov_b32 m0, s11
	s_add_u32 s11, s11, 0x2000
	global_load_lds_dwordx4 v68, s[12:13]
	s_add_u32 s12, s12, 0x10000
	s_addc_u32 s13, s13, 0
	s_waitcnt vmcnt(0)
	s_barrier
	ds_read_b128 v[84:87], v70 offset:0
	ds_read_b128 v[88:91], v70 offset:8192
	ds_read_b128 v[92:95], v74 offset:0
	ds_read_b128 v[96:99], v74 offset:8192
	ds_read_b128 v[100:103], v74 offset:16384
	ds_read_b128 v[104:107], v74 offset:24576
	ds_read_b128 v[108:111], v71 offset:0
	ds_read_b128 v[112:115], v71 offset:8192
	ds_read_b128 v[116:119], v75 offset:0
	ds_read_b128 v[120:123], v75 offset:8192
	ds_read_b128 v[124:127], v75 offset:16384
	ds_read_b128 v[128:131], v75 offset:24576
	s_waitcnt lgkmcnt(6)
	v_mfma_f32_16x16x32_bf16 v[16:19], v[92:95], v[84:87], 0
	v_mfma_f32_16x16x32_bf16 v[20:23], v[96:99], v[84:87], 0
	v_mfma_f32_16x16x32_bf16 v[24:27], v[100:103], v[84:87], 0
	v_mfma_f32_16x16x32_bf16 v[28:31], v[104:107], v[84:87], 0
	v_mfma_f32_16x16x32_bf16 v[48:51], v[92:95], v[88:91], 0
	v_mfma_f32_16x16x32_bf16 v[52:55], v[96:99], v[88:91], 0
	v_mfma_f32_16x16x32_bf16 v[56:59], v[100:103], v[88:91], 0
	v_mfma_f32_16x16x32_bf16 v[60:63], v[104:107], v[88:91], 0
	ds_read_b128 v[84:87], v72 offset:0
	ds_read_b128 v[88:91], v72 offset:8192
	ds_read_b128 v[92:95], v76 offset:0
	ds_read_b128 v[96:99], v76 offset:8192
	ds_read_b128 v[100:103], v76 offset:16384
	ds_read_b128 v[104:107], v76 offset:24576
	s_waitcnt lgkmcnt(6)
	v_mfma_f32_16x16x32_bf16 v[16:19], v[116:119], v[108:111], v[16:19]
	v_mfma_f32_16x16x32_bf16 v[20:23], v[120:123], v[108:111], v[20:23]
	v_mfma_f32_16x16x32_bf16 v[24:27], v[124:127], v[108:111], v[24:27]
	v_mfma_f32_16x16x32_bf16 v[28:31], v[128:131], v[108:111], v[28:31]
	v_mfma_f32_16x16x32_bf16 v[48:51], v[116:119], v[112:115], v[48:51]
	v_mfma_f32_16x16x32_bf16 v[52:55], v[120:123], v[112:115], v[52:55]
	v_mfma_f32_16x16x32_bf16 v[56:59], v[124:127], v[112:115], v[56:59]
	v_mfma_f32_16x16x32_bf16 v[60:63], v[128:131], v[112:115], v[60:63]
	ds_read_b128 v[108:111], v73 offset:0
	ds_read_b128 v[112:115], v73 offset:8192
	ds_read_b128 v[116:119], v77 offset:0
	ds_read_b128 v[120:123], v77 offset:8192
	ds_read_b128 v[124:127], v77 offset:16384
	ds_read_b128 v[128:131], v77 offset:24576
	s_waitcnt lgkmcnt(6)
	v_mfma_f32_16x16x32_bf16 v[16:19], v[92:95], v[84:87], v[16:19]
	v_mfma_f32_16x16x32_bf16 v[20:23], v[96:99], v[84:87], v[20:23]
	v_mfma_f32_16x16x32_bf16 v[24:27], v[100:103], v[84:87], v[24:27]
	v_mfma_f32_16x16x32_bf16 v[28:31], v[104:107], v[84:87], v[28:31]
	v_mfma_f32_16x16x32_bf16 v[48:51], v[92:95], v[88:91], v[48:51]
	v_mfma_f32_16x16x32_bf16 v[52:55], v[96:99], v[88:91], v[52:55]
	v_mfma_f32_16x16x32_bf16 v[56:59], v[100:103], v[88:91], v[56:59]
	v_mfma_f32_16x16x32_bf16 v[60:63], v[104:107], v[88:91], v[60:63]
	ds_read_b128 v[84:87], v70 offset:256
	ds_read_b128 v[88:91], v70 offset:8448
	ds_read_b128 v[92:95], v74 offset:256
	ds_read_b128 v[96:99], v74 offset:8448
	ds_read_b128 v[100:103], v74 offset:16640
	ds_read_b128 v[104:107], v74 offset:24832
	s_waitcnt lgkmcnt(6)
	v_mfma_f32_16x16x32_bf16 v[16:19], v[116:119], v[108:111], v[16:19]
	v_mfma_f32_16x16x32_bf16 v[20:23], v[120:123], v[108:111], v[20:23]
	v_mfma_f32_16x16x32_bf16 v[24:27], v[124:127], v[108:111], v[24:27]
	v_mfma_f32_16x16x32_bf16 v[28:31], v[128:131], v[108:111], v[28:31]
	v_mfma_f32_16x16x32_bf16 v[48:51], v[116:119], v[112:115], v[48:51]
	v_mfma_f32_16x16x32_bf16 v[52:55], v[120:123], v[112:115], v[52:55]
	v_mfma_f32_16x16x32_bf16 v[56:59], v[124:127], v[112:115], v[56:59]
	v_mfma_f32_16x16x32_bf16 v[60:63], v[128:131], v[112:115], v[60:63]
	ds_read_b128 v[108:111], v71 offset:256
	ds_read_b128 v[112:115], v71 offset:8448
	ds_read_b128 v[116:119], v75 offset:256
	ds_read_b128 v[120:123], v75 offset:8448
	ds_read_b128 v[124:127], v75 offset:16640
	ds_read_b128 v[128:131], v75 offset:24832
	s_waitcnt lgkmcnt(6)
	v_mfma_f32_16x16x32_bf16 v[16:19], v[92:95], v[84:87], v[16:19]
	v_mfma_f32_16x16x32_bf16 v[20:23], v[96:99], v[84:87], v[20:23]
	v_mfma_f32_16x16x32_bf16 v[24:27], v[100:103], v[84:87], v[24:27]
	v_mfma_f32_16x16x32_bf16 v[28:31], v[104:107], v[84:87], v[28:31]
	v_mfma_f32_16x16x32_bf16 v[48:51], v[92:95], v[88:91], v[48:51]
	v_mfma_f32_16x16x32_bf16 v[52:55], v[96:99], v[88:91], v[52:55]
	v_mfma_f32_16x16x32_bf16 v[56:59], v[100:103], v[88:91], v[56:59]
	v_mfma_f32_16x16x32_bf16 v[60:63], v[104:107], v[88:91], v[60:63]
	ds_read_b128 v[84:87], v72 offset:256
	ds_read_b128 v[88:91], v72 offset:8448
	ds_read_b128 v[92:95], v76 offset:256
	ds_read_b128 v[96:99], v76 offset:8448
	ds_read_b128 v[100:103], v76 offset:16640
	ds_read_b128 v[104:107], v76 offset:24832
	s_waitcnt lgkmcnt(6)
	v_mfma_f32_16x16x32_bf16 v[16:19], v[116:119], v[108:111], v[16:19]
	v_mfma_f32_16x16x32_bf16 v[20:23], v[120:123], v[108:111], v[20:23]
	v_mfma_f32_16x16x32_bf16 v[24:27], v[124:127], v[108:111], v[24:27]
	v_mfma_f32_16x16x32_bf16 v[28:31], v[128:131], v[108:111], v[28:31]
	v_mfma_f32_16x16x32_bf16 v[48:51], v[116:119], v[112:115], v[48:51]
	v_mfma_f32_16x16x32_bf16 v[52:55], v[120:123], v[112:115], v[52:55]
	v_mfma_f32_16x16x32_bf16 v[56:59], v[124:127], v[112:115], v[56:59]
	v_mfma_f32_16x16x32_bf16 v[60:63], v[128:131], v[112:115], v[60:63]
	ds_read_b128 v[108:111], v73 offset:256
	ds_read_b128 v[112:115], v73 offset:8448
	ds_read_b128 v[116:119], v77 offset:256
	ds_read_b128 v[120:123], v77 offset:8448
	ds_read_b128 v[124:127], v77 offset:16640
	ds_read_b128 v[128:131], v77 offset:24832
	s_waitcnt lgkmcnt(6)
	v_mfma_f32_16x16x32_bf16 v[16:19], v[92:95], v[84:87], v[16:19]
	v_mfma_f32_16x16x32_bf16 v[20:23], v[96:99], v[84:87], v[20:23]
	v_mfma_f32_16x16x32_bf16 v[24:27], v[100:103], v[84:87], v[24:27]
	v_mfma_f32_16x16x32_bf16 v[28:31], v[104:107], v[84:87], v[28:31]
	v_mfma_f32_16x16x32_bf16 v[48:51], v[92:95], v[88:91], v[48:51]
	v_mfma_f32_16x16x32_bf16 v[52:55], v[96:99], v[88:91], v[52:55]
	v_mfma_f32_16x16x32_bf16 v[56:59], v[100:103], v[88:91], v[56:59]
	v_mfma_f32_16x16x32_bf16 v[60:63], v[104:107], v[88:91], v[60:63]
	s_waitcnt lgkmcnt(0)
	v_mfma_f32_16x16x32_bf16 v[16:19], v[116:119], v[108:111], v[16:19]
	v_mfma_f32_16x16x32_bf16 v[20:23], v[120:123], v[108:111], v[20:23]
	v_mfma_f32_16x16x32_bf16 v[24:27], v[124:127], v[108:111], v[24:27]
	v_mfma_f32_16x16x32_bf16 v[28:31], v[128:131], v[108:111], v[28:31]
	v_mfma_f32_16x16x32_bf16 v[48:51], v[116:119], v[112:115], v[48:51]
	v_mfma_f32_16x16x32_bf16 v[52:55], v[120:123], v[112:115], v[52:55]
	v_mfma_f32_16x16x32_bf16 v[56:59], v[124:127], v[112:115], v[56:59]
	v_mfma_f32_16x16x32_bf16 v[60:63], v[128:131], v[112:115], v[60:63]
	s_nop 7
	global_store_dwordx4 v69, v[0:3], s[18:19] offset:0
	global_store_dwordx4 v69, v[4:7], s[18:19] offset:64
	global_store_dwordx4 v69, v[8:11], s[18:19] offset:128
	global_store_dwordx4 v69, v[12:15], s[18:19] offset:192
	global_store_dwordx4 v69, v[16:19], s[18:19] offset:512
	global_store_dwordx4 v69, v[20:23], s[18:19] offset:576
	global_store_dwordx4 v69, v[24:27], s[18:19] offset:640
	global_store_dwordx4 v69, v[28:31], s[18:19] offset:704
	global_store_dwordx4 v69, v[32:35], s[42:43] offset:0
	global_store_dwordx4 v69, v[36:39], s[42:43] offset:64
	global_store_dwordx4 v69, v[40:43], s[42:43] offset:128
	global_store_dwordx4 v69, v[44:47], s[42:43] offset:192
	global_store_dwordx4 v69, v[48:51], s[42:43] offset:512
	global_store_dwordx4 v69, v[52:55], s[42:43] offset:576
	global_store_dwordx4 v69, v[56:59], s[42:43] offset:640
	global_store_dwordx4 v69, v[60:63], s[42:43] offset:704
	s_barrier
.Lmain_9:
	v_lshlrev_b32_e32 v0, 4, v231
	v_and_b32_e32 v2, 4, v237
	v_and_b32_e32 v137, 24, v238
	s_movk_i32 s6, 0x70
	v_bitop3_b32 v8, v0, v239, 48 bitop3:0x6c
	v_or3_b32 v2, v2, v235, v137
	v_and_or_b32 v3, v236, s6, v234
	s_movk_i32 s6, 0x60
	v_add_u32_e32 v9, 0x2000, v0
	v_or_b32_e32 v1, v8, v139
	v_and_or_b32 v4, v236, s6, v2
	v_lshrrev_b32_e32 v0, 7, v9
	s_movk_i32 s6, 0xf0
	v_lshl_or_b32 v128, v3, 12, v1
	v_and_or_b32 v3, v0, s6, v234
	s_movk_i32 s6, 0xe0
	s_add_u32 s3, s28, 0x5800000
	v_and_or_b32 v0, v0, s6, v2
	s_addc_u32 s62, s29, 0
	v_lshl_or_b32 v130, v4, 12, v1
	v_lshl_or_b32 v132, v3, 12, v1
	v_lshl_or_b32 v134, v0, 12, v1
	v_lshlrev_b32_e32 v153, 1, v137
	v_and_b32_e32 v0, 0x3c0, v233
	v_and_b32_e32 v1, 32, v138
	s_ashr_i32 s63, s34, 31
	s_ashr_i32 s64, s2, 31
	v_mov_b32_e32 v131, 0
	v_bitop3_b32 v152, v153, v1, v0 bitop3:0x36
	s_cmpk_gt_i32 s2, 0xff
	v_mov_b32_e32 v135, v131
	v_mov_b32_e32 v129, v131
	v_mov_b32_e32 v133, v131
	v_readfirstlane_b32 s7, v231
	s_cbranch_scc1 .LBB0_1656
	s_add_u32 s17, s28, 0x2bf00000
	s_addc_u32 s36, s29, 0
	s_lshr_b32 s6, s64, 29
	s_add_i32 s6, s2, s6
	s_and_b32 s10, s6, -8
	s_lshr_b32 s15, s7, 6
	s_sub_i32 s10, s2, s10
	s_lshr_b32 s14, s7, 8
	s_lshl_b32 s37, s15, 10
	s_lshl_b32 s12, s10, 5
	s_ashr_i32 s6, s6, 3
	s_mul_i32 s11, s10, 33
	s_cmp_lt_i32 s10, 0
	s_cselect_b32 s10, s11, s12
	s_add_i32 s6, s10, s6
	s_ashr_i32 s10, s6, 31
	s_lshr_b32 s10, s10, 26
	s_add_i32 s10, s6, s10
	s_ashr_i32 s11, s10, 6
	s_andn2_b32 s10, s10, 63
	s_sub_i32 s10, s6, s10
	s_bfe_i32 s6, s10, 0x80000
	s_bfe_u32 s6, s6, 0x3000c
	s_add_i32 s12, s10, s6
	s_bfe_i32 s6, s12, 0x80000
	s_and_b32 s12, s12, 0xf8
	s_sub_i32 s10, s10, s12
	s_lshl_b32 s11, s11, 3
	s_sext_i32_i8 s10, s10
	s_add_i32 s12, s11, s10
	s_sext_i32_i16 s6, s6
	s_ashr_i32 s13, s12, 31
	s_lshr_b32 s6, s6, 3
	s_lshl_b64 s[10:11], s[12:13], 20
	s_add_u32 s22, s17, s10
	s_addc_u32 s23, s36, s11
	s_bfe_i64 s[10:11], s[6:7], 0x100000
	s_lshl_b64 s[10:11], s[10:11], 20
	s_add_u32 s24, s3, s10
	s_addc_u32 s25, s62, s11
	s_add_i32 s38, s37, 0
	s_add_i32 m0, s38, 0x10000
	v_lshl_add_u64 v[0:1], s[24:25], 0, v[130:131]
	global_load_lds_dwordx4 v[0:1], off
	s_add_i32 m0, s38, 0x12000
	s_add_u32 s10, s24, 0x80000
	v_lshl_add_u64 v[2:3], s[24:25], 0, v[134:135]
	s_addc_u32 s11, s25, 0
	global_load_lds_dwordx4 v[2:3], off
	s_add_i32 m0, s38, 0x14000
	v_lshl_add_u64 v[4:5], s[10:11], 0, v[130:131]
	global_load_lds_dwordx4 v[4:5], off
	v_lshl_add_u64 v[4:5], s[10:11], 0, v[134:135]
	s_add_i32 m0, s38, 0x16000
	s_add_i32 s39, s38, 0x2000
	global_load_lds_dwordx4 v[4:5], off
	v_lshl_add_u64 v[6:7], s[22:23], 0, v[128:129]
	s_mov_b32 m0, s38
	s_add_u32 s10, s22, 0x80000
	global_load_lds_dwordx4 v[6:7], off
	v_lshl_add_u64 v[4:5], s[22:23], 0, v[132:133]
	s_mov_b32 m0, s39
	s_addc_u32 s11, s23, 0
	s_add_i32 s40, s38, 0x4000
	global_load_lds_dwordx4 v[4:5], off
	v_lshl_add_u64 v[10:11], s[10:11], 0, v[128:129]
	s_mov_b32 m0, s40
	s_add_i32 s41, s38, 0x6000
	global_load_lds_dwordx4 v[10:11], off
	v_lshl_add_u64 v[10:11], s[10:11], 0, v[132:133]
	s_mov_b32 m0, s41
	s_cmp_eq_u32 s14, 1
	global_load_lds_dwordx4 v[10:11], off
	s_cselect_b64 s[10:11], -1, 0
	s_cmp_lg_u32 s14, 1
	s_mov_b32 s42, 0
	s_cbranch_scc1 .LBB0_1639
	s_barrier

.LBB0_1656:
	s_cmp_gt_i32 s2, 63
	v_readfirstlane_b32 s10, v231
.LBB0_1672:
	s_cmp_gt_i32 s31, 10
	s_cselect_b64 s[6:7], -1, 0
	s_and_b64 s[8:9], s[8:9], s[6:7]
	s_andn2_b64 vcc, exec, s[8:9]
	s_cbranch_vccnz .LBB0_1726
	s_waitcnt vmcnt(0)
	s_waitcnt vmcnt(0) lgkmcnt(0)
	s_barrier
	s_and_saveexec_b64 s[8:9], s[4:5]
	s_cbranch_execz .LBB0_1725
	s_add_i32 s3, 0, 0x20000
	v_mov_b32_e32 v0, s3
	s_waitcnt vmcnt(0) expcnt(0) lgkmcnt(0)
	ds_read_b32 v2, v0
	s_add_i32 s3, 0, 0x20004
	v_mov_b32_e32 v0, s3
	ds_read_b32 v0, v0
	s_waitcnt lgkmcnt(1)
	v_cmp_ne_u32_e32 vcc, 0, v2
	s_cbranch_vccnz .LBB0_1689
	s_add_u32 s10, s28, 0x30300200
	s_addc_u32 s11, s29, 0
	s_add_u32 s12, s28, 0x30300400
	s_addc_u32 s13, s29, 0
	s_add_u32 s14, s28, 0x30300500
	s_addc_u32 s15, s29, 0
	s_add_u32 s16, s28, 0x30300600
	s_addc_u32 s17, s29, 0
	s_add_u32 s18, s28, 0x30300700
	s_addc_u32 s19, s29, 0
	s_add_u32 s20, s28, 0x30300800
	s_addc_u32 s21, s29, 0
	s_add_u32 s22, s28, 0x30300900
	s_addc_u32 s23, s29, 0
	s_add_u32 s24, s28, 0x30300a00
	s_addc_u32 s25, s29, 0
	s_add_u32 s26, s28, 0x30300b00
	s_addc_u32 s27, s29, 0
	s_add_u32 s36, s28, 0x30300c00
	s_addc_u32 s37, s29, 0
	s_add_u32 s38, s28, 0x30300d00
	s_addc_u32 s39, s29, 0
	s_add_u32 s40, s28, 0x30300e00
	s_addc_u32 s41, s29, 0
	s_add_u32 s42, s28, 0x30300f00
	s_addc_u32 s43, s29, 0
	s_add_u32 s44, s28, 0x30301000
	s_addc_u32 s45, s29, 0
	s_add_u32 s46, s28, 0x30301100
	s_addc_u32 s47, s29, 0
	s_add_u32 s58, s28, 0x30301200
	s_addc_u32 s59, s29, 0
	s_mul_i32 s3, s35, s82
	s_add_u32 s60, s28, 0x30301300
	s_mul_i32 s3, s3, s34
	s_addc_u32 s61, s29, 0
	s_mov_b32 s68, 1
	v_mov_b32_e32 v16, 0
	s_branch .LBB0_1677

.LBB0_1792:
	s_cmp_lt_i32 s30, 12
	s_cselect_b64 s[8:9], -1, 0
	s_and_b64 s[8:9], s[8:9], s[6:7]
	s_andn2_b64 vcc, exec, s[8:9]
	s_cbranch_vccnz .LBB0_1848
	s_cmp_gt_i32 s2, 63
	s_cbranch_scc1 .Lmain_11
	v_and_b32_e32 v64, 63, v231
	v_and_b32_e32 v65, 15, v64
	v_bfe_u32 v66, v64, 4, 2
	v_readfirstlane_b32 s44, v230
	s_and_b32 s60, s2, 7
	s_lshr_b32 s61, s2, 3
	s_lshl_b32 s63, s61, 9
	s_nop 0
	s_and_b32 s40, s44, 3
	s_lshr_b32 s59, s44, 2
	v_and_b32_e32 v67, 3, v65
	v_xor_b32_e32 v67, v66, v67
	v_lshlrev_b32_e32 v67, 4, v67
	v_lshl_add_u32 v67, v65, 9, v67
	v_lshrrev_b32_e32 v69, 2, v65
	s_lshl_b32 s64, s40, 14
	s_lshl_b32 s76, s59, 15
	s_add_u32 s76, s76, 0x10000
	v_xor_b32_e32 v70, 0, v69
	v_lshl_add_u32 v70, v70, 6, v67
	v_add_u32_e32 v74, s76, v70
	v_add_u32_e32 v70, s64, v70
	v_xor_b32_e32 v71, 1, v69
	v_lshl_add_u32 v71, v71, 6, v67
	v_add_u32_e32 v75, s76, v71
	v_add_u32_e32 v71, s64, v71
	v_xor_b32_e32 v72, 2, v69
	v_lshl_add_u32 v72, v72, 6, v67
	v_add_u32_e32 v76, s76, v72
	v_add_u32_e32 v72, s64, v72
	v_xor_b32_e32 v73, 3, v69
	v_lshl_add_u32 v73, v73, 6, v67
	v_add_u32_e32 v77, s76, v73
	v_add_u32_e32 v73, s64, v73
	v_lshrrev_b32_e32 v68, 5, v64
	s_lshl_b32 s77, s44, 1
	v_add_u32_e32 v69, s77, v68
	v_and_b32_e32 v67, 31, v64
	v_xor_b32_e32 v67, v67, v69
	v_lshlrev_b32_e32 v67, 4, v67
	v_mul_u32_u24_e32 v68, 0x1000, v68
	v_add_u32_e32 v68, v68, v67
	v_lshlrev_b32_e32 v69, 13, v65
	v_lshl_add_u32 v69, v66, 4, v69
	s_lshl_b32 s62, s44, 1
	s_mul_i32 s62, s62, 0x1000
	s_add_u32 s14, s28, 0xc500000
	s_addc_u32 s15, s29, 0
	s_add_u32 s14, s14, 0x2000000
	s_addc_u32 s15, s15, 0
	s_add_u32 s14, s14, s62
	s_addc_u32 s15, s15, 0
	s_add_u32 s14, s14, s63
	s_addc_u32 s15, s15, 0
	s_lshl_b32 s64, s60, 8
	s_mul_i32 s64, s64, 0x1000
	s_add_u32 s16, s28, 0x6000000
	s_addc_u32 s17, s29, 0
	s_add_u32 s16, s16, s64
	s_addc_u32 s17, s17, 0
	s_add_u32 s16, s16, s62
	s_addc_u32 s17, s17, 0
	s_add_u32 s16, s16, s63
	s_addc_u32 s17, s17, 0
	s_lshl_b32 s76, s61, 7
	s_lshl_b32 s77, s40, 5
	s_add_u32 s76, s76, s77
	s_lshl_b32 s76, s76, 13
	s_lshl_b32 s77, s60, 10
	s_lshl_b32 s3, s59, 8
	s_add_u32 s76, s76, s77
	s_add_u32 s76, s76, s3
	s_add_u32 s18, s28, 0x2ec00000
	s_addc_u32 s19, s29, 0
	s_add_u32 s18, s18, s76
	s_addc_u32 s19, s19, 0
	s_add_u32 s42, s18, 0x20000
	s_addc_u32 s43, s19, 0
	s_lshl_b32 s62, s44, 10
	s_mov_b64 s[12:13], s[14:15]
	s_add_u32 s11, s62, 0x0
	s_mov_b32 m0, s11
	s_add_u32 s11, s11, 0x2000
	global_load_lds_dwordx4 v68, s[12:13]
	s_add_u32 s12, s12, 0x10000
	s_addc_u32 s13, s13, 0
	s_mov_b32 m0, s11
	s_add_u32 s11, s11, 0x2000
	global_load_lds_dwordx4 v68, s[12:13]
	s_add_u32 s12, s12, 0x10000
	s_addc_u32 s13, s13, 0
	s_mov_b32 m0, s11
	s_add_u32 s11, s11, 0x2000
	global_load_lds_dwordx4 v68, s[12:13]
	s_add_u32 s12, s12, 0x10000
	s_addc_u32 s13, s13, 0
	s_mov_b32 m0, s11
	s_add_u32 s11, s11, 0x2000
	global_load_lds_dwordx4 v68, s[12:13]
	s_add_u32 s12, s12, 0x10000
	s_addc_u32 s13, s13, 0
	s_mov_b32 m0, s11
	s_add_u32 s11, s11, 0x2000
	global_load_lds_dwordx4 v68, s[12:13]
	s_add_u32 s12, s12, 0x10000
	s_addc_u32 s13, s13, 0
	s_mov_b32 m0, s11
	s_add_u32 s11, s11, 0x2000
	global_load_lds_dwordx4 v68, s[12:13]
	s_add_u32 s12, s12, 0x10000
	s_addc_u32 s13, s13, 0
	s_mov_b32 m0, s11
	s_add_u32 s11, s11, 0x2000
	global_load_lds_dwordx4 v68, s[12:13]
	s_add_u32 s12, s12, 0x10000
	s_addc_u32 s13, s13, 0
	s_mov_b32 m0, s11
	s_add_u32 s11, s11, 0x2000
	global_load_lds_dwordx4 v68, s[12:13]
	s_add_u32 s12, s12, 0x10000
	s_addc_u32 s13, s13, 0
	s_mov_b64 s[12:13], s[16:17]
	s_add_u32 s11, s62, 0x10000
	s_mov_b32 m0, s11
	s_add_u32 s11, s11, 0x2000
	global_load_lds_dwordx4 v68, s[12:13]
	s_add_u32 s12, s12, 0x10000
	s_addc_u32 s13, s13, 0
	s_mov_b32 m0, s11
	s_add_u32 s11, s11, 0x2000
	global_load_lds_dwordx4 v68, s[12:13]
	s_add_u32 s12, s12, 0x10000
	s_addc_u32 s13, s13, 0
	s_mov_b32 m0, s11
	s_add_u32 s11, s11, 0x2000
	global_load_lds_dwordx4 v68, s[12:13]
	s_add_u32 s12, s12, 0x10000
	s_addc_u32 s13, s13, 0
	s_mov_b32 m0, s11
	s_add_u32 s11, s11, 0x2000
	global_load_lds_dwordx4 v68, s[12:13]
	s_add_u32 s12, s12, 0x10000
	s_addc_u32 s13, s13, 0
	s_mov_b32 m0, s11
	s_add_u32 s11, s11, 0x2000
	global_load_lds_dwordx4 v68, s[12:13]
	s_add_u32 s12, s12, 0x10000
	s_addc_u32 s13, s13, 0
	s_mov_b32 m0, s11
	s_add_u32 s11, s11, 0x2000
	global_load_lds_dwordx4 v68, s[12:13]
	s_add_u32 s12, s12, 0x10000
	s_addc_u32 s13, s13, 0
	s_mov_b32 m0, s11
	s_add_u32 s11, s11, 0x2000
	global_load_lds_dwordx4 v68, s[12:13]
	s_add_u32 s12, s12, 0x10000
	s_addc_u32 s13, s13, 0
	s_mov_b32 m0, s11
	s_add_u32 s11, s11, 0x2000
	global_load_lds_dwordx4 v68, s[12:13]
	s_add_u32 s12, s12, 0x10000
	s_addc_u32 s13, s13, 0
	s_add_u32 s16, s16, 0x80000
	s_addc_u32 s17, s17, 0
	s_waitcnt vmcnt(0)
	s_barrier
	ds_read_b128 v[84:87], v70 offset:0
	ds_read_b128 v[88:91], v70 offset:8192
	ds_read_b128 v[92:95], v74 offset:0
	ds_read_b128 v[96:99], v74 offset:8192
	ds_read_b128 v[100:103], v74 offset:16384
	ds_read_b128 v[104:107], v74 offset:24576
	ds_read_b128 v[108:111], v71 offset:0
	ds_read_b128 v[112:115], v71 offset:8192
	ds_read_b128 v[116:119], v75 offset:0
	ds_read_b128 v[120:123], v75 offset:8192
	ds_read_b128 v[124:127], v75 offset:16384
	ds_read_b128 v[128:131], v75 offset:24576
	s_waitcnt lgkmcnt(6)
	v_mfma_f32_16x16x32_bf16 v[0:3], v[92:95], v[84:87], 0
	v_mfma_f32_16x16x32_bf16 v[4:7], v[96:99], v[84:87], 0
	v_mfma_f32_16x16x32_bf16 v[8:11], v[100:103], v[84:87], 0
	v_mfma_f32_16x16x32_bf16 v[12:15], v[104:107], v[84:87], 0
	v_mfma_f32_16x16x32_bf16 v[32:35], v[92:95], v[88:91], 0
	v_mfma_f32_16x16x32_bf16 v[36:39], v[96:99], v[88:91], 0
	v_mfma_f32_16x16x32_bf16 v[40:43], v[100:103], v[88:91], 0
	v_mfma_f32_16x16x32_bf16 v[44:47], v[104:107], v[88:91], 0
	ds_read_b128 v[84:87], v72 offset:0
	ds_read_b128 v[88:91], v72 offset:8192
	ds_read_b128 v[92:95], v76 offset:0
	ds_read_b128 v[96:99], v76 offset:8192
	ds_read_b128 v[100:103], v76 offset:16384
	ds_read_b128 v[104:107], v76 offset:24576
	s_waitcnt lgkmcnt(6)
	v_mfma_f32_16x16x32_bf16 v[0:3], v[116:119], v[108:111], v[0:3]
	v_mfma_f32_16x16x32_bf16 v[4:7], v[120:123], v[108:111], v[4:7]
	v_mfma_f32_16x16x32_bf16 v[8:11], v[124:127], v[108:111], v[8:11]
	v_mfma_f32_16x16x32_bf16 v[12:15], v[128:131], v[108:111], v[12:15]
	v_mfma_f32_16x16x32_bf16 v[32:35], v[116:119], v[112:115], v[32:35]
	v_mfma_f32_16x16x32_bf16 v[36:39], v[120:123], v[112:115], v[36:39]
	v_mfma_f32_16x16x32_bf16 v[40:43], v[124:127], v[112:115], v[40:43]
	v_mfma_f32_16x16x32_bf16 v[44:47], v[128:131], v[112:115], v[44:47]
	ds_read_b128 v[108:111], v73 offset:0
	ds_read_b128 v[112:115], v73 offset:8192
	ds_read_b128 v[116:119], v77 offset:0
	ds_read_b128 v[120:123], v77 offset:8192
	ds_read_b128 v[124:127], v77 offset:16384
	ds_read_b128 v[128:131], v77 offset:24576
	s_waitcnt lgkmcnt(6)
	v_mfma_f32_16x16x32_bf16 v[0:3], v[92:95], v[84:87], v[0:3]
	v_mfma_f32_16x16x32_bf16 v[4:7], v[96:99], v[84:87], v[4:7]
	v_mfma_f32_16x16x32_bf16 v[8:11], v[100:103], v[84:87], v[8:11]
	v_mfma_f32_16x16x32_bf16 v[12:15], v[104:107], v[84:87], v[12:15]
	v_mfma_f32_16x16x32_bf16 v[32:35], v[92:95], v[88:91], v[32:35]
	v_mfma_f32_16x16x32_bf16 v[36:39], v[96:99], v[88:91], v[36:39]
	v_mfma_f32_16x16x32_bf16 v[40:43], v[100:103], v[88:91], v[40:43]
	v_mfma_f32_16x16x32_bf16 v[44:47], v[104:107], v[88:91], v[44:47]
	ds_read_b128 v[84:87], v70 offset:256
	ds_read_b128 v[88:91], v70 offset:8448
	ds_read_b128 v[92:95], v74 offset:256
	ds_read_b128 v[96:99], v74 offset:8448
	ds_read_b128 v[100:103], v74 offset:16640
	ds_read_b128 v[104:107], v74 offset:24832
	s_waitcnt lgkmcnt(6)
	v_mfma_f32_16x16x32_bf16 v[0:3], v[116:119], v[108:111], v[0:3]
	v_mfma_f32_16x16x32_bf16 v[4:7], v[120:123], v[108:111], v[4:7]
	v_mfma_f32_16x16x32_bf16 v[8:11], v[124:127], v[108:111], v[8:11]
	v_mfma_f32_16x16x32_bf16 v[12:15], v[128:131], v[108:111], v[12:15]
	v_mfma_f32_16x16x32_bf16 v[32:35], v[116:119], v[112:115], v[32:35]
	v_mfma_f32_16x16x32_bf16 v[36:39], v[120:123], v[112:115], v[36:39]
	v_mfma_f32_16x16x32_bf16 v[40:43], v[124:127], v[112:115], v[40:43]
	v_mfma_f32_16x16x32_bf16 v[44:47], v[128:131], v[112:115], v[44:47]
	ds_read_b128 v[108:111], v71 offset:256
	ds_read_b128 v[112:115], v71 offset:8448
	ds_read_b128 v[116:119], v75 offset:256
	ds_read_b128 v[120:123], v75 offset:8448
	ds_read_b128 v[124:127], v75 offset:16640
	ds_read_b128 v[128:131], v75 offset:24832
	s_waitcnt lgkmcnt(6)
	v_mfma_f32_16x16x32_bf16 v[0:3], v[92:95], v[84:87], v[0:3]
	v_mfma_f32_16x16x32_bf16 v[4:7], v[96:99], v[84:87], v[4:7]
	v_mfma_f32_16x16x32_bf16 v[8:11], v[100:103], v[84:87], v[8:11]
	v_mfma_f32_16x16x32_bf16 v[12:15], v[104:107], v[84:87], v[12:15]
	v_mfma_f32_16x16x32_bf16 v[32:35], v[92:95], v[88:91], v[32:35]
	v_mfma_f32_16x16x32_bf16 v[36:39], v[96:99], v[88:91], v[36:39]
	v_mfma_f32_16x16x32_bf16 v[40:43], v[100:103], v[88:91], v[40:43]
	v_mfma_f32_16x16x32_bf16 v[44:47], v[104:107], v[88:91], v[44:47]
	ds_read_b128 v[84:87], v72 offset:256
	ds_read_b128 v[88:91], v72 offset:8448
	ds_read_b128 v[92:95], v76 offset:256
	ds_read_b128 v[96:99], v76 offset:8448
	ds_read_b128 v[100:103], v76 offset:16640
	ds_read_b128 v[104:107], v76 offset:24832
	s_waitcnt lgkmcnt(6)
	v_mfma_f32_16x16x32_bf16 v[0:3], v[116:119], v[108:111], v[0:3]
	v_mfma_f32_16x16x32_bf16 v[4:7], v[120:123], v[108:111], v[4:7]
	v_mfma_f32_16x16x32_bf16 v[8:11], v[124:127], v[108:111], v[8:11]
	v_mfma_f32_16x16x32_bf16 v[12:15], v[128:131], v[108:111], v[12:15]
	v_mfma_f32_16x16x32_bf16 v[32:35], v[116:119], v[112:115], v[32:35]
	v_mfma_f32_16x16x32_bf16 v[36:39], v[120:123], v[112:115], v[36:39]
	v_mfma_f32_16x16x32_bf16 v[40:43], v[124:127], v[112:115], v[40:43]
	v_mfma_f32_16x16x32_bf16 v[44:47], v[128:131], v[112:115], v[44:47]
	ds_read_b128 v[108:111], v73 offset:256
	ds_read_b128 v[112:115], v73 offset:8448
	ds_read_b128 v[116:119], v77 offset:256
	ds_read_b128 v[120:123], v77 offset:8448
	ds_read_b128 v[124:127], v77 offset:16640
	ds_read_b128 v[128:131], v77 offset:24832
	s_waitcnt lgkmcnt(6)
	v_mfma_f32_16x16x32_bf16 v[0:3], v[92:95], v[84:87], v[0:3]
	v_mfma_f32_16x16x32_bf16 v[4:7], v[96:99], v[84:87], v[4:7]
	v_mfma_f32_16x16x32_bf16 v[8:11], v[100:103], v[84:87], v[8:11]
	v_mfma_f32_16x16x32_bf16 v[12:15], v[104:107], v[84:87], v[12:15]
	v_mfma_f32_16x16x32_bf16 v[32:35], v[92:95], v[88:91], v[32:35]
	v_mfma_f32_16x16x32_bf16 v[36:39], v[96:99], v[88:91], v[36:39]
	v_mfma_f32_16x16x32_bf16 v[40:43], v[100:103], v[88:91], v[40:43]
	v_mfma_f32_16x16x32_bf16 v[44:47], v[104:107], v[88:91], v[44:47]
	s_waitcnt lgkmcnt(0)
	v_mfma_f32_16x16x32_bf16 v[0:3], v[116:119], v[108:111], v[0:3]
	v_mfma_f32_16x16x32_bf16 v[4:7], v[120:123], v[108:111], v[4:7]
	v_mfma_f32_16x16x32_bf16 v[8:11], v[124:127], v[108:111], v[8:11]
	v_mfma_f32_16x16x32_bf16 v[12:15], v[128:131], v[108:111], v[12:15]
	v_mfma_f32_16x16x32_bf16 v[32:35], v[116:119], v[112:115], v[32:35]
	v_mfma_f32_16x16x32_bf16 v[36:39], v[120:123], v[112:115], v[36:39]
	v_mfma_f32_16x16x32_bf16 v[40:43], v[124:127], v[112:115], v[40:43]
	v_mfma_f32_16x16x32_bf16 v[44:47], v[128:131], v[112:115], v[44:47]
	s_barrier
	s_mov_b64 s[12:13], s[16:17]
	s_add_u32 s11, s62, 0x10000
	s_mov_b32 m0, s11
	s_add_u32 s11, s11, 0x2000
	global_load_lds_dwordx4 v68, s[12:13]
	s_add_u32 s12, s12, 0x10000
	s_addc_u32 s13, s13, 0
	s_mov_b32 m0, s11
	s_add_u32 s11, s11, 0x2000
	global_load_lds_dwordx4 v68, s[12:13]
	s_add_u32 s12, s12, 0x10000
	s_addc_u32 s13, s13, 0
	s_mov_b32 m0, s11
	s_add_u32 s11, s11, 0x2000
	global_load_lds_dwordx4 v68, s[12:13]
	s_add_u32 s12, s12, 0x10000
	s_addc_u32 s13, s13, 0
	s_mov_b32 m0, s11
	s_add_u32 s11, s11, 0x2000
	global_load_lds_dwordx4 v68, s[12:13]
	s_add_u32 s12, s12, 0x10000
	s_addc_u32 s13, s13, 0
	s_mov_b32 m0, s11
	s_add_u32 s11, s11, 0x2000
	global_load_lds_dwordx4 v68, s[12:13]
	s_add_u32 s12, s12, 0x10000
	s_addc_u32 s13, s13, 0
	s_mov_b32 m0, s11
	s_add_u32 s11, s11, 0x2000
	global_load_lds_dwordx4 v68, s[12:13]
	s_add_u32 s12, s12, 0x10000
	s_addc_u32 s13, s13, 0
	s_mov_b32 m0, s11
	s_add_u32 s11, s11, 0x2000
	global_load_lds_dwordx4 v68, s[12:13]
	s_add_u32 s12, s12, 0x10000
	s_addc_u32 s13, s13, 0
	s_mov_b32 m0, s11
	s_add_u32 s11, s11, 0x2000
	global_load_lds_dwordx4 v68, s[12:13]
	s_add_u32 s12, s12, 0x10000
	s_addc_u32 s13, s13, 0
	s_waitcnt vmcnt(0)
	s_barrier
	ds_read_b128 v[84:87], v70 offset:0
	ds_read_b128 v[88:91], v70 offset:8192
	ds_read_b128 v[92:95], v74 offset:0
	ds_read_b128 v[96:99], v74 offset:8192
	ds_read_b128 v[100:103], v74 offset:16384
	ds_read_b128 v[104:107], v74 offset:24576
	ds_read_b128 v[108:111], v71 offset:0
	ds_read_b128 v[112:115], v71 offset:8192
	ds_read_b128 v[116:119], v75 offset:0
	ds_read_b128 v[120:123], v75 offset:8192
	ds_read_b128 v[124:127], v75 offset:16384
	ds_read_b128 v[128:131], v75 offset:24576
	s_waitcnt lgkmcnt(6)
	v_mfma_f32_16x16x32_bf16 v[16:19], v[92:95], v[84:87], 0
	v_mfma_f32_16x16x32_bf16 v[20:23], v[96:99], v[84:87], 0
	v_mfma_f32_16x16x32_bf16 v[24:27], v[100:103], v[84:87], 0
	v_mfma_f32_16x16x32_bf16 v[28:31], v[104:107], v[84:87], 0
	v_mfma_f32_16x16x32_bf16 v[48:51], v[92:95], v[88:91], 0
	v_mfma_f32_16x16x32_bf16 v[52:55], v[96:99], v[88:91], 0
	v_mfma_f32_16x16x32_bf16 v[56:59], v[100:103], v[88:91], 0
	v_mfma_f32_16x16x32_bf16 v[60:63], v[104:107], v[88:91], 0
	ds_read_b128 v[84:87], v72 offset:0
	ds_read_b128 v[88:91], v72 offset:8192
	ds_read_b128 v[92:95], v76 offset:0
	ds_read_b128 v[96:99], v76 offset:8192
	ds_read_b128 v[100:103], v76 offset:16384
	ds_read_b128 v[104:107], v76 offset:24576
	s_waitcnt lgkmcnt(6)
	v_mfma_f32_16x16x32_bf16 v[16:19], v[116:119], v[108:111], v[16:19]
	v_mfma_f32_16x16x32_bf16 v[20:23], v[120:123], v[108:111], v[20:23]
	v_mfma_f32_16x16x32_bf16 v[24:27], v[124:127], v[108:111], v[24:27]
	v_mfma_f32_16x16x32_bf16 v[28:31], v[128:131], v[108:111], v[28:31]
	v_mfma_f32_16x16x32_bf16 v[48:51], v[116:119], v[112:115], v[48:51]
	v_mfma_f32_16x16x32_bf16 v[52:55], v[120:123], v[112:115], v[52:55]
	v_mfma_f32_16x16x32_bf16 v[56:59], v[124:127], v[112:115], v[56:59]
	v_mfma_f32_16x16x32_bf16 v[60:63], v[128:131], v[112:115], v[60:63]
	ds_read_b128 v[108:111], v73 offset:0
	ds_read_b128 v[112:115], v73 offset:8192
	ds_read_b128 v[116:119], v77 offset:0
	ds_read_b128 v[120:123], v77 offset:8192
	ds_read_b128 v[124:127], v77 offset:16384
	ds_read_b128 v[128:131], v77 offset:24576
	s_waitcnt lgkmcnt(6)
	v_mfma_f32_16x16x32_bf16 v[16:19], v[92:95], v[84:87], v[16:19]
	v_mfma_f32_16x16x32_bf16 v[20:23], v[96:99], v[84:87], v[20:23]
	v_mfma_f32_16x16x32_bf16 v[24:27], v[100:103], v[84:87], v[24:27]
	v_mfma_f32_16x16x32_bf16 v[28:31], v[104:107], v[84:87], v[28:31]
	v_mfma_f32_16x16x32_bf16 v[48:51], v[92:95], v[88:91], v[48:51]
	v_mfma_f32_16x16x32_bf16 v[52:55], v[96:99], v[88:91], v[52:55]
	v_mfma_f32_16x16x32_bf16 v[56:59], v[100:103], v[88:91], v[56:59]
	v_mfma_f32_16x16x32_bf16 v[60:63], v[104:107], v[88:91], v[60:63]
	ds_read_b128 v[84:87], v70 offset:256
	ds_read_b128 v[88:91], v70 offset:8448
	ds_read_b128 v[92:95], v74 offset:256
	ds_read_b128 v[96:99], v74 offset:8448
	ds_read_b128 v[100:103], v74 offset:16640
	ds_read_b128 v[104:107], v74 offset:24832
	s_waitcnt lgkmcnt(6)
	v_mfma_f32_16x16x32_bf16 v[16:19], v[116:119], v[108:111], v[16:19]
	v_mfma_f32_16x16x32_bf16 v[20:23], v[120:123], v[108:111], v[20:23]
	v_mfma_f32_16x16x32_bf16 v[24:27], v[124:127], v[108:111], v[24:27]
	v_mfma_f32_16x16x32_bf16 v[28:31], v[128:131], v[108:111], v[28:31]
	v_mfma_f32_16x16x32_bf16 v[48:51], v[116:119], v[112:115], v[48:51]
	v_mfma_f32_16x16x32_bf16 v[52:55], v[120:123], v[112:115], v[52:55]
	v_mfma_f32_16x16x32_bf16 v[56:59], v[124:127], v[112:115], v[56:59]
	v_mfma_f32_16x16x32_bf16 v[60:63], v[128:131], v[112:115], v[60:63]
	ds_read_b128 v[108:111], v71 offset:256
	ds_read_b128 v[112:115], v71 offset:8448
	ds_read_b128 v[116:119], v75 offset:256
	ds_read_b128 v[120:123], v75 offset:8448
	ds_read_b128 v[124:127], v75 offset:16640
	ds_read_b128 v[128:131], v75 offset:24832
	s_waitcnt lgkmcnt(6)
	v_mfma_f32_16x16x32_bf16 v[16:19], v[92:95], v[84:87], v[16:19]
	v_mfma_f32_16x16x32_bf16 v[20:23], v[96:99], v[84:87], v[20:23]
	v_mfma_f32_16x16x32_bf16 v[24:27], v[100:103], v[84:87], v[24:27]
	v_mfma_f32_16x16x32_bf16 v[28:31], v[104:107], v[84:87], v[28:31]
	v_mfma_f32_16x16x32_bf16 v[48:51], v[92:95], v[88:91], v[48:51]
	v_mfma_f32_16x16x32_bf16 v[52:55], v[96:99], v[88:91], v[52:55]
	v_mfma_f32_16x16x32_bf16 v[56:59], v[100:103], v[88:91], v[56:59]
	v_mfma_f32_16x16x32_bf16 v[60:63], v[104:107], v[88:91], v[60:63]
	ds_read_b128 v[84:87], v72 offset:256
	ds_read_b128 v[88:91], v72 offset:8448
	ds_read_b128 v[92:95], v76 offset:256
	ds_read_b128 v[96:99], v76 offset:8448
	ds_read_b128 v[100:103], v76 offset:16640
	ds_read_b128 v[104:107], v76 offset:24832
	s_waitcnt lgkmcnt(6)
	v_mfma_f32_16x16x32_bf16 v[16:19], v[116:119], v[108:111], v[16:19]
	v_mfma_f32_16x16x32_bf16 v[20:23], v[120:123], v[108:111], v[20:23]
	v_mfma_f32_16x16x32_bf16 v[24:27], v[124:127], v[108:111], v[24:27]
	v_mfma_f32_16x16x32_bf16 v[28:31], v[128:131], v[108:111], v[28:31]
	v_mfma_f32_16x16x32_bf16 v[48:51], v[116:119], v[112:115], v[48:51]
	v_mfma_f32_16x16x32_bf16 v[52:55], v[120:123], v[112:115], v[52:55]
	v_mfma_f32_16x16x32_bf16 v[56:59], v[124:127], v[112:115], v[56:59]
	v_mfma_f32_16x16x32_bf16 v[60:63], v[128:131], v[112:115], v[60:63]
	ds_read_b128 v[108:111], v73 offset:256
	ds_read_b128 v[112:115], v73 offset:8448
	ds_read_b128 v[116:119], v77 offset:256
	ds_read_b128 v[120:123], v77 offset:8448
	ds_read_b128 v[124:127], v77 offset:16640
	ds_read_b128 v[128:131], v77 offset:24832
	s_waitcnt lgkmcnt(6)
	v_mfma_f32_16x16x32_bf16 v[16:19], v[92:95], v[84:87], v[16:19]
	v_mfma_f32_16x16x32_bf16 v[20:23], v[96:99], v[84:87], v[20:23]
	v_mfma_f32_16x16x32_bf16 v[24:27], v[100:103], v[84:87], v[24:27]
	v_mfma_f32_16x16x32_bf16 v[28:31], v[104:107], v[84:87], v[28:31]
	v_mfma_f32_16x16x32_bf16 v[48:51], v[92:95], v[88:91], v[48:51]
	v_mfma_f32_16x16x32_bf16 v[52:55], v[96:99], v[88:91], v[52:55]
	v_mfma_f32_16x16x32_bf16 v[56:59], v[100:103], v[88:91], v[56:59]
	v_mfma_f32_16x16x32_bf16 v[60:63], v[104:107], v[88:91], v[60:63]
	s_waitcnt lgkmcnt(0)
	v_mfma_f32_16x16x32_bf16 v[16:19], v[116:119], v[108:111], v[16:19]
	v_mfma_f32_16x16x32_bf16 v[20:23], v[120:123], v[108:111], v[20:23]
	v_mfma_f32_16x16x32_bf16 v[24:27], v[124:127], v[108:111], v[24:27]
	v_mfma_f32_16x16x32_bf16 v[28:31], v[128:131], v[108:111], v[28:31]
	v_mfma_f32_16x16x32_bf16 v[48:51], v[116:119], v[112:115], v[48:51]
	v_mfma_f32_16x16x32_bf16 v[52:55], v[120:123], v[112:115], v[52:55]
	v_mfma_f32_16x16x32_bf16 v[56:59], v[124:127], v[112:115], v[56:59]
	v_mfma_f32_16x16x32_bf16 v[60:63], v[128:131], v[112:115], v[60:63]
	s_nop 7
	global_store_dwordx4 v69, v[0:3], s[18:19] offset:0
	global_store_dwordx4 v69, v[4:7], s[18:19] offset:64
	global_store_dwordx4 v69, v[8:11], s[18:19] offset:128
	global_store_dwordx4 v69, v[12:15], s[18:19] offset:192
	global_store_dwordx4 v69, v[16:19], s[18:19] offset:512
	global_store_dwordx4 v69, v[20:23], s[18:19] offset:576
	global_store_dwordx4 v69, v[24:27], s[18:19] offset:640
	global_store_dwordx4 v69, v[28:31], s[18:19] offset:704
	global_store_dwordx4 v69, v[32:35], s[42:43] offset:0
	global_store_dwordx4 v69, v[36:39], s[42:43] offset:64
	global_store_dwordx4 v69, v[40:43], s[42:43] offset:128
	global_store_dwordx4 v69, v[44:47], s[42:43] offset:192
	global_store_dwordx4 v69, v[48:51], s[42:43] offset:512
	global_store_dwordx4 v69, v[52:55], s[42:43] offset:576
	global_store_dwordx4 v69, v[56:59], s[42:43] offset:640
	global_store_dwordx4 v69, v[60:63], s[42:43] offset:704
	s_barrier
.Lmain_11:
	s_add_u32 s3, s28, 0x6000000
	s_addc_u32 s62, s29, 0
	s_cmpk_lt_i32 s2, 0x100
	s_cselect_b64 s[6:7], -1, 0
	s_cmpk_gt_i32 s2, 0xff
	v_readfirstlane_b32 s11, v231
	s_cbranch_scc1 .LBB0_1795
	s_ashr_i32 s10, s2, 31
	s_lshr_b32 s10, s10, 29
	s_add_i32 s10, s2, s10
	s_waitcnt lgkmcnt(0)
	s_and_b32 s12, s10, -8
	s_sub_i32 s12, s2, s12
	s_lshl_b32 s14, s12, 5
	s_ashr_i32 s10, s10, 3
	s_mul_i32 s13, s12, 33
	s_cmp_lt_i32 s12, 0
	s_cselect_b32 s12, s13, s14
	s_add_i32 s10, s12, s10
	s_ashr_i32 s12, s10, 31
	s_lshr_b32 s12, s12, 26
	s_add_i32 s12, s10, s12
	s_ashr_i32 s13, s12, 6
	s_andn2_b32 s12, s12, 63
	s_sub_i32 s12, s10, s12
	s_bfe_i32 s10, s12, 0x80000
	s_bfe_u32 s10, s10, 0x3000c
	s_add_i32 s14, s12, s10
	s_bfe_i32 s10, s14, 0x80000
	s_and_b32 s14, s14, 0xf8
	s_sub_i32 s12, s12, s14
	s_lshl_b32 s13, s13, 3
	s_sext_i32_i8 s12, s12
	s_add_i32 s12, s13, s12
	s_sext_i32_i16 s10, s10
	s_ashr_i32 s13, s12, 31
	s_lshr_b32 s10, s10, 3
	s_lshl_b64 s[14:15], s[12:13], 20
	s_add_u32 s36, s50, s14
	s_addc_u32 s37, s51, s15
	s_bfe_i64 s[14:15], s[10:11], 0x100000
	s_lshl_b64 s[14:15], s[14:15], 20
	s_add_u32 s38, s3, s14
	s_addc_u32 s39, s62, s15
	s_lshl_b32 s68, s12, 8
	s_lshl_b32 s10, s10, 8
	s_branch .LBB0_1796

.LBB0_1832:
	s_cmp_gt_i32 s2, 63
	v_readfirstlane_b32 s10, v231
.LBB0_1848:
	s_cmp_gt_i32 s31, 12
	s_cselect_b64 s[6:7], -1, 0
	s_and_b64 s[8:9], s[8:9], s[6:7]
	s_andn2_b64 vcc, exec, s[8:9]
	s_cbranch_vccnz .LBB0_1902
	s_waitcnt vmcnt(0)
	s_waitcnt vmcnt(0) lgkmcnt(0)
	s_barrier
	s_and_saveexec_b64 s[8:9], s[4:5]
	s_cbranch_execz .LBB0_1901
	s_add_i32 s3, 0, 0x20000
	v_mov_b32_e32 v0, s3
	s_waitcnt vmcnt(0) expcnt(0) lgkmcnt(0)
	ds_read_b32 v2, v0
	s_add_i32 s3, 0, 0x20004
	v_mov_b32_e32 v0, s3
	ds_read_b32 v0, v0
	s_waitcnt lgkmcnt(1)
	v_cmp_ne_u32_e32 vcc, 0, v2
	s_cbranch_vccnz .LBB0_1865
	s_add_u32 s10, s28, 0x30300200
	s_addc_u32 s11, s29, 0
	s_add_u32 s12, s28, 0x30300400
	s_addc_u32 s13, s29, 0
	s_add_u32 s14, s28, 0x30300500
	s_addc_u32 s15, s29, 0
	s_add_u32 s16, s28, 0x30300600
	s_addc_u32 s17, s29, 0
	s_add_u32 s18, s28, 0x30300700
	s_addc_u32 s19, s29, 0
	s_add_u32 s20, s28, 0x30300800
	s_addc_u32 s21, s29, 0
	s_add_u32 s22, s28, 0x30300900
	s_addc_u32 s23, s29, 0
	s_add_u32 s24, s28, 0x30300a00
	s_addc_u32 s25, s29, 0
	s_add_u32 s26, s28, 0x30300b00
	s_addc_u32 s27, s29, 0
	s_add_u32 s36, s28, 0x30300c00
	s_addc_u32 s37, s29, 0
	s_add_u32 s38, s28, 0x30300d00
	s_addc_u32 s39, s29, 0
	s_add_u32 s40, s28, 0x30300e00
	s_addc_u32 s41, s29, 0
	s_add_u32 s42, s28, 0x30300f00
	s_addc_u32 s43, s29, 0
	s_add_u32 s44, s28, 0x30301000
	s_addc_u32 s45, s29, 0
	s_add_u32 s46, s28, 0x30301100
	s_addc_u32 s47, s29, 0
	s_add_u32 s58, s28, 0x30301200
	s_addc_u32 s59, s29, 0
	s_mul_i32 s3, s35, s82
	s_add_u32 s60, s28, 0x30301300
	s_mul_i32 s3, s3, s34
	s_addc_u32 s61, s29, 0
	s_mov_b32 s68, 1
	v_mov_b32_e32 v16, 0
	s_branch .LBB0_1853

.LBB0_2112:
	s_cmp_lt_i32 s30, 15
	s_cselect_b64 s[8:9], -1, 0
	s_and_b64 s[8:9], s[8:9], s[6:7]
	s_andn2_b64 vcc, exec, s[8:9]
	s_cbranch_vccnz .LBB0_2149
	s_cmp_gt_i32 s2, 63
	s_cbranch_scc1 .Lmain_14
	v_and_b32_e32 v64, 63, v231
	v_and_b32_e32 v65, 15, v64
	v_bfe_u32 v66, v64, 4, 2
	v_readfirstlane_b32 s44, v230
	s_and_b32 s60, s2, 7
	s_lshr_b32 s61, s2, 3
	s_lshl_b32 s63, s61, 9
	s_nop 0
	s_and_b32 s40, s44, 3
	s_lshr_b32 s59, s44, 2
	v_and_b32_e32 v67, 3, v65
	v_xor_b32_e32 v67, v66, v67
	v_lshlrev_b32_e32 v67, 4, v67
	v_lshl_add_u32 v67, v65, 9, v67
	v_lshrrev_b32_e32 v69, 2, v65
	s_lshl_b32 s64, s40, 14
	s_lshl_b32 s76, s59, 15
	s_add_u32 s76, s76, 0x10000
	v_xor_b32_e32 v70, 0, v69
	v_lshl_add_u32 v70, v70, 6, v67
	v_add_u32_e32 v74, s76, v70
	v_add_u32_e32 v70, s64, v70
	v_xor_b32_e32 v71, 1, v69
	v_lshl_add_u32 v71, v71, 6, v67
	v_add_u32_e32 v75, s76, v71
	v_add_u32_e32 v71, s64, v71
	v_xor_b32_e32 v72, 2, v69
	v_lshl_add_u32 v72, v72, 6, v67
	v_add_u32_e32 v76, s76, v72
	v_add_u32_e32 v72, s64, v72
	v_xor_b32_e32 v73, 3, v69
	v_lshl_add_u32 v73, v73, 6, v67
	v_add_u32_e32 v77, s76, v73
	v_add_u32_e32 v73, s64, v73
	v_lshrrev_b32_e32 v68, 5, v64
	s_lshl_b32 s77, s44, 1
	v_add_u32_e32 v69, s77, v68
	v_and_b32_e32 v67, 31, v64
	v_xor_b32_e32 v67, v67, v69
	v_lshlrev_b32_e32 v67, 4, v67
	v_mul_u32_u24_e32 v68, 0x1000, v68
	v_add_u32_e32 v68, v68, v67
	v_lshlrev_b32_e32 v69, 13, v65
	v_lshl_add_u32 v69, v66, 4, v69
	s_lshl_b32 s62, s44, 1
	s_mul_i32 s62, s62, 0x1000
	s_add_u32 s14, s28, 0x19a00000
	s_addc_u32 s15, s29, 0
	s_add_u32 s14, s14, 0x2000000
	s_addc_u32 s15, s15, 0
	s_add_u32 s14, s14, s62
	s_addc_u32 s15, s15, 0
	s_add_u32 s14, s14, s63
	s_addc_u32 s15, s15, 0
	s_lshl_b32 s64, s60, 8
	s_mul_i32 s64, s64, 0x1000
	s_add_u32 s16, s28, 0x7800000
	s_addc_u32 s17, s29, 0
	s_add_u32 s16, s16, s64
	s_addc_u32 s17, s17, 0
	s_add_u32 s16, s16, s62
	s_addc_u32 s17, s17, 0
	s_add_u32 s16, s16, s63
	s_addc_u32 s17, s17, 0
	s_lshl_b32 s76, s61, 7
	s_lshl_b32 s77, s40, 5
	s_add_u32 s76, s76, s77
	s_lshl_b32 s76, s76, 13
	s_lshl_b32 s77, s60, 10
	s_lshl_b32 s3, s59, 8
	s_add_u32 s76, s76, s77
	s_add_u32 s76, s76, s3
	s_add_u32 s18, s28, 0x2ec00000
	s_addc_u32 s19, s29, 0
	s_add_u32 s18, s18, s76
	s_addc_u32 s19, s19, 0
	s_add_u32 s42, s18, 0x20000
	s_addc_u32 s43, s19, 0
	s_lshl_b32 s62, s44, 10
	s_mov_b64 s[12:13], s[14:15]
	s_add_u32 s11, s62, 0x0
	s_mov_b32 m0, s11
	s_add_u32 s11, s11, 0x2000
	global_load_lds_dwordx4 v68, s[12:13]
	s_add_u32 s12, s12, 0x10000
	s_addc_u32 s13, s13, 0
	s_mov_b32 m0, s11
	s_add_u32 s11, s11, 0x2000
	global_load_lds_dwordx4 v68, s[12:13]
	s_add_u32 s12, s12, 0x10000
	s_addc_u32 s13, s13, 0
	s_mov_b32 m0, s11
	s_add_u32 s11, s11, 0x2000
	global_load_lds_dwordx4 v68, s[12:13]
	s_add_u32 s12, s12, 0x10000
	s_addc_u32 s13, s13, 0
	s_mov_b32 m0, s11
	s_add_u32 s11, s11, 0x2000
	global_load_lds_dwordx4 v68, s[12:13]
	s_add_u32 s12, s12, 0x10000
	s_addc_u32 s13, s13, 0
	s_mov_b32 m0, s11
	s_add_u32 s11, s11, 0x2000
	global_load_lds_dwordx4 v68, s[12:13]
	s_add_u32 s12, s12, 0x10000
	s_addc_u32 s13, s13, 0
	s_mov_b32 m0, s11
	s_add_u32 s11, s11, 0x2000
	global_load_lds_dwordx4 v68, s[12:13]
	s_add_u32 s12, s12, 0x10000
	s_addc_u32 s13, s13, 0
	s_mov_b32 m0, s11
	s_add_u32 s11, s11, 0x2000
	global_load_lds_dwordx4 v68, s[12:13]
	s_add_u32 s12, s12, 0x10000
	s_addc_u32 s13, s13, 0
	s_mov_b32 m0, s11
	s_add_u32 s11, s11, 0x2000
	global_load_lds_dwordx4 v68, s[12:13]
	s_add_u32 s12, s12, 0x10000
	s_addc_u32 s13, s13, 0
	s_mov_b64 s[12:13], s[16:17]
	s_add_u32 s11, s62, 0x10000
	s_mov_b32 m0, s11
	s_add_u32 s11, s11, 0x2000
	global_load_lds_dwordx4 v68, s[12:13]
	s_add_u32 s12, s12, 0x10000
	s_addc_u32 s13, s13, 0
	s_mov_b32 m0, s11
	s_add_u32 s11, s11, 0x2000
	global_load_lds_dwordx4 v68, s[12:13]
	s_add_u32 s12, s12, 0x10000
	s_addc_u32 s13, s13, 0
	s_mov_b32 m0, s11
	s_add_u32 s11, s11, 0x2000
	global_load_lds_dwordx4 v68, s[12:13]
	s_add_u32 s12, s12, 0x10000
	s_addc_u32 s13, s13, 0
	s_mov_b32 m0, s11
	s_add_u32 s11, s11, 0x2000
	global_load_lds_dwordx4 v68, s[12:13]
	s_add_u32 s12, s12, 0x10000
	s_addc_u32 s13, s13, 0
	s_mov_b32 m0, s11
	s_add_u32 s11, s11, 0x2000
	global_load_lds_dwordx4 v68, s[12:13]
	s_add_u32 s12, s12, 0x10000
	s_addc_u32 s13, s13, 0
	s_mov_b32 m0, s11
	s_add_u32 s11, s11, 0x2000
	global_load_lds_dwordx4 v68, s[12:13]
	s_add_u32 s12, s12, 0x10000
	s_addc_u32 s13, s13, 0
	s_mov_b32 m0, s11
	s_add_u32 s11, s11, 0x2000
	global_load_lds_dwordx4 v68, s[12:13]
	s_add_u32 s12, s12, 0x10000
	s_addc_u32 s13, s13, 0
	s_mov_b32 m0, s11
	s_add_u32 s11, s11, 0x2000
	global_load_lds_dwordx4 v68, s[12:13]
	s_add_u32 s12, s12, 0x10000
	s_addc_u32 s13, s13, 0
	s_add_u32 s16, s16, 0x80000
	s_addc_u32 s17, s17, 0
	s_waitcnt vmcnt(0)
	s_barrier
	ds_read_b128 v[84:87], v70 offset:0
	ds_read_b128 v[88:91], v70 offset:8192
	ds_read_b128 v[92:95], v74 offset:0
	ds_read_b128 v[96:99], v74 offset:8192
	ds_read_b128 v[100:103], v74 offset:16384
	ds_read_b128 v[104:107], v74 offset:24576
	ds_read_b128 v[108:111], v71 offset:0
	ds_read_b128 v[112:115], v71 offset:8192
	ds_read_b128 v[116:119], v75 offset:0
	ds_read_b128 v[120:123], v75 offset:8192
	ds_read_b128 v[124:127], v75 offset:16384
	ds_read_b128 v[128:131], v75 offset:24576
	s_waitcnt lgkmcnt(6)
	v_mfma_f32_16x16x32_bf16 v[0:3], v[92:95], v[84:87], 0
	v_mfma_f32_16x16x32_bf16 v[4:7], v[96:99], v[84:87], 0
	v_mfma_f32_16x16x32_bf16 v[8:11], v[100:103], v[84:87], 0
	v_mfma_f32_16x16x32_bf16 v[12:15], v[104:107], v[84:87], 0
	v_mfma_f32_16x16x32_bf16 v[32:35], v[92:95], v[88:91], 0
	v_mfma_f32_16x16x32_bf16 v[36:39], v[96:99], v[88:91], 0
	v_mfma_f32_16x16x32_bf16 v[40:43], v[100:103], v[88:91], 0
	v_mfma_f32_16x16x32_bf16 v[44:47], v[104:107], v[88:91], 0
	ds_read_b128 v[84:87], v72 offset:0
	ds_read_b128 v[88:91], v72 offset:8192
	ds_read_b128 v[92:95], v76 offset:0
	ds_read_b128 v[96:99], v76 offset:8192
	ds_read_b128 v[100:103], v76 offset:16384
	ds_read_b128 v[104:107], v76 offset:24576
	s_waitcnt lgkmcnt(6)
	v_mfma_f32_16x16x32_bf16 v[0:3], v[116:119], v[108:111], v[0:3]
	v_mfma_f32_16x16x32_bf16 v[4:7], v[120:123], v[108:111], v[4:7]
	v_mfma_f32_16x16x32_bf16 v[8:11], v[124:127], v[108:111], v[8:11]
	v_mfma_f32_16x16x32_bf16 v[12:15], v[128:131], v[108:111], v[12:15]
	v_mfma_f32_16x16x32_bf16 v[32:35], v[116:119], v[112:115], v[32:35]
	v_mfma_f32_16x16x32_bf16 v[36:39], v[120:123], v[112:115], v[36:39]
	v_mfma_f32_16x16x32_bf16 v[40:43], v[124:127], v[112:115], v[40:43]
	v_mfma_f32_16x16x32_bf16 v[44:47], v[128:131], v[112:115], v[44:47]
	ds_read_b128 v[108:111], v73 offset:0
	ds_read_b128 v[112:115], v73 offset:8192
	ds_read_b128 v[116:119], v77 offset:0
	ds_read_b128 v[120:123], v77 offset:8192
	ds_read_b128 v[124:127], v77 offset:16384
	ds_read_b128 v[128:131], v77 offset:24576
	s_waitcnt lgkmcnt(6)
	v_mfma_f32_16x16x32_bf16 v[0:3], v[92:95], v[84:87], v[0:3]
	v_mfma_f32_16x16x32_bf16 v[4:7], v[96:99], v[84:87], v[4:7]
	v_mfma_f32_16x16x32_bf16 v[8:11], v[100:103], v[84:87], v[8:11]
	v_mfma_f32_16x16x32_bf16 v[12:15], v[104:107], v[84:87], v[12:15]
	v_mfma_f32_16x16x32_bf16 v[32:35], v[92:95], v[88:91], v[32:35]
	v_mfma_f32_16x16x32_bf16 v[36:39], v[96:99], v[88:91], v[36:39]
	v_mfma_f32_16x16x32_bf16 v[40:43], v[100:103], v[88:91], v[40:43]
	v_mfma_f32_16x16x32_bf16 v[44:47], v[104:107], v[88:91], v[44:47]
	ds_read_b128 v[84:87], v70 offset:256
	ds_read_b128 v[88:91], v70 offset:8448
	ds_read_b128 v[92:95], v74 offset:256
	ds_read_b128 v[96:99], v74 offset:8448
	ds_read_b128 v[100:103], v74 offset:16640
	ds_read_b128 v[104:107], v74 offset:24832
	s_waitcnt lgkmcnt(6)
	v_mfma_f32_16x16x32_bf16 v[0:3], v[116:119], v[108:111], v[0:3]
	v_mfma_f32_16x16x32_bf16 v[4:7], v[120:123], v[108:111], v[4:7]
	v_mfma_f32_16x16x32_bf16 v[8:11], v[124:127], v[108:111], v[8:11]
	v_mfma_f32_16x16x32_bf16 v[12:15], v[128:131], v[108:111], v[12:15]
	v_mfma_f32_16x16x32_bf16 v[32:35], v[116:119], v[112:115], v[32:35]
	v_mfma_f32_16x16x32_bf16 v[36:39], v[120:123], v[112:115], v[36:39]
	v_mfma_f32_16x16x32_bf16 v[40:43], v[124:127], v[112:115], v[40:43]
	v_mfma_f32_16x16x32_bf16 v[44:47], v[128:131], v[112:115], v[44:47]
	ds_read_b128 v[108:111], v71 offset:256
	ds_read_b128 v[112:115], v71 offset:8448
	ds_read_b128 v[116:119], v75 offset:256
	ds_read_b128 v[120:123], v75 offset:8448
	ds_read_b128 v[124:127], v75 offset:16640
	ds_read_b128 v[128:131], v75 offset:24832
	s_waitcnt lgkmcnt(6)
	v_mfma_f32_16x16x32_bf16 v[0:3], v[92:95], v[84:87], v[0:3]
	v_mfma_f32_16x16x32_bf16 v[4:7], v[96:99], v[84:87], v[4:7]
	v_mfma_f32_16x16x32_bf16 v[8:11], v[100:103], v[84:87], v[8:11]
	v_mfma_f32_16x16x32_bf16 v[12:15], v[104:107], v[84:87], v[12:15]
	v_mfma_f32_16x16x32_bf16 v[32:35], v[92:95], v[88:91], v[32:35]
	v_mfma_f32_16x16x32_bf16 v[36:39], v[96:99], v[88:91], v[36:39]
	v_mfma_f32_16x16x32_bf16 v[40:43], v[100:103], v[88:91], v[40:43]
	v_mfma_f32_16x16x32_bf16 v[44:47], v[104:107], v[88:91], v[44:47]
	ds_read_b128 v[84:87], v72 offset:256
	ds_read_b128 v[88:91], v72 offset:8448
	ds_read_b128 v[92:95], v76 offset:256
	ds_read_b128 v[96:99], v76 offset:8448
	ds_read_b128 v[100:103], v76 offset:16640
	ds_read_b128 v[104:107], v76 offset:24832
	s_waitcnt lgkmcnt(6)
	v_mfma_f32_16x16x32_bf16 v[0:3], v[116:119], v[108:111], v[0:3]
	v_mfma_f32_16x16x32_bf16 v[4:7], v[120:123], v[108:111], v[4:7]
	v_mfma_f32_16x16x32_bf16 v[8:11], v[124:127], v[108:111], v[8:11]
	v_mfma_f32_16x16x32_bf16 v[12:15], v[128:131], v[108:111], v[12:15]
	v_mfma_f32_16x16x32_bf16 v[32:35], v[116:119], v[112:115], v[32:35]
	v_mfma_f32_16x16x32_bf16 v[36:39], v[120:123], v[112:115], v[36:39]
	v_mfma_f32_16x16x32_bf16 v[40:43], v[124:127], v[112:115], v[40:43]
	v_mfma_f32_16x16x32_bf16 v[44:47], v[128:131], v[112:115], v[44:47]
	ds_read_b128 v[108:111], v73 offset:256
	ds_read_b128 v[112:115], v73 offset:8448
	ds_read_b128 v[116:119], v77 offset:256
	ds_read_b128 v[120:123], v77 offset:8448
	ds_read_b128 v[124:127], v77 offset:16640
	ds_read_b128 v[128:131], v77 offset:24832
	s_waitcnt lgkmcnt(6)
	v_mfma_f32_16x16x32_bf16 v[0:3], v[92:95], v[84:87], v[0:3]
	v_mfma_f32_16x16x32_bf16 v[4:7], v[96:99], v[84:87], v[4:7]
	v_mfma_f32_16x16x32_bf16 v[8:11], v[100:103], v[84:87], v[8:11]
	v_mfma_f32_16x16x32_bf16 v[12:15], v[104:107], v[84:87], v[12:15]
	v_mfma_f32_16x16x32_bf16 v[32:35], v[92:95], v[88:91], v[32:35]
	v_mfma_f32_16x16x32_bf16 v[36:39], v[96:99], v[88:91], v[36:39]
	v_mfma_f32_16x16x32_bf16 v[40:43], v[100:103], v[88:91], v[40:43]
	v_mfma_f32_16x16x32_bf16 v[44:47], v[104:107], v[88:91], v[44:47]
	s_waitcnt lgkmcnt(0)
	v_mfma_f32_16x16x32_bf16 v[0:3], v[116:119], v[108:111], v[0:3]
	v_mfma_f32_16x16x32_bf16 v[4:7], v[120:123], v[108:111], v[4:7]
	v_mfma_f32_16x16x32_bf16 v[8:11], v[124:127], v[108:111], v[8:11]
	v_mfma_f32_16x16x32_bf16 v[12:15], v[128:131], v[108:111], v[12:15]
	v_mfma_f32_16x16x32_bf16 v[32:35], v[116:119], v[112:115], v[32:35]
	v_mfma_f32_16x16x32_bf16 v[36:39], v[120:123], v[112:115], v[36:39]
	v_mfma_f32_16x16x32_bf16 v[40:43], v[124:127], v[112:115], v[40:43]
	v_mfma_f32_16x16x32_bf16 v[44:47], v[128:131], v[112:115], v[44:47]
	s_barrier
	s_mov_b64 s[12:13], s[16:17]
	s_add_u32 s11, s62, 0x10000
	s_mov_b32 m0, s11
	s_add_u32 s11, s11, 0x2000
	global_load_lds_dwordx4 v68, s[12:13]
	s_add_u32 s12, s12, 0x10000
	s_addc_u32 s13, s13, 0
	s_mov_b32 m0, s11
	s_add_u32 s11, s11, 0x2000
	global_load_lds_dwordx4 v68, s[12:13]
	s_add_u32 s12, s12, 0x10000
	s_addc_u32 s13, s13, 0
	s_mov_b32 m0, s11
	s_add_u32 s11, s11, 0x2000
	global_load_lds_dwordx4 v68, s[12:13]
	s_add_u32 s12, s12, 0x10000
	s_addc_u32 s13, s13, 0
	s_mov_b32 m0, s11
	s_add_u32 s11, s11, 0x2000
	global_load_lds_dwordx4 v68, s[12:13]
	s_add_u32 s12, s12, 0x10000
	s_addc_u32 s13, s13, 0
	s_mov_b32 m0, s11
	s_add_u32 s11, s11, 0x2000
	global_load_lds_dwordx4 v68, s[12:13]
	s_add_u32 s12, s12, 0x10000
	s_addc_u32 s13, s13, 0
	s_mov_b32 m0, s11
	s_add_u32 s11, s11, 0x2000
	global_load_lds_dwordx4 v68, s[12:13]
	s_add_u32 s12, s12, 0x10000
	s_addc_u32 s13, s13, 0
	s_mov_b32 m0, s11
	s_add_u32 s11, s11, 0x2000
	global_load_lds_dwordx4 v68, s[12:13]
	s_add_u32 s12, s12, 0x10000
	s_addc_u32 s13, s13, 0
	s_mov_b32 m0, s11
	s_add_u32 s11, s11, 0x2000
	global_load_lds_dwordx4 v68, s[12:13]
	s_add_u32 s12, s12, 0x10000
	s_addc_u32 s13, s13, 0
	s_waitcnt vmcnt(0)
	s_barrier
	ds_read_b128 v[84:87], v70 offset:0
	ds_read_b128 v[88:91], v70 offset:8192
	ds_read_b128 v[92:95], v74 offset:0
	ds_read_b128 v[96:99], v74 offset:8192
	ds_read_b128 v[100:103], v74 offset:16384
	ds_read_b128 v[104:107], v74 offset:24576
	ds_read_b128 v[108:111], v71 offset:0
	ds_read_b128 v[112:115], v71 offset:8192
	ds_read_b128 v[116:119], v75 offset:0
	ds_read_b128 v[120:123], v75 offset:8192
	ds_read_b128 v[124:127], v75 offset:16384
	ds_read_b128 v[128:131], v75 offset:24576
	s_waitcnt lgkmcnt(6)
	v_mfma_f32_16x16x32_bf16 v[16:19], v[92:95], v[84:87], 0
	v_mfma_f32_16x16x32_bf16 v[20:23], v[96:99], v[84:87], 0
	v_mfma_f32_16x16x32_bf16 v[24:27], v[100:103], v[84:87], 0
	v_mfma_f32_16x16x32_bf16 v[28:31], v[104:107], v[84:87], 0
	v_mfma_f32_16x16x32_bf16 v[48:51], v[92:95], v[88:91], 0
	v_mfma_f32_16x16x32_bf16 v[52:55], v[96:99], v[88:91], 0
	v_mfma_f32_16x16x32_bf16 v[56:59], v[100:103], v[88:91], 0
	v_mfma_f32_16x16x32_bf16 v[60:63], v[104:107], v[88:91], 0
	ds_read_b128 v[84:87], v72 offset:0
	ds_read_b128 v[88:91], v72 offset:8192
	ds_read_b128 v[92:95], v76 offset:0
	ds_read_b128 v[96:99], v76 offset:8192
	ds_read_b128 v[100:103], v76 offset:16384
	ds_read_b128 v[104:107], v76 offset:24576
	s_waitcnt lgkmcnt(6)
	v_mfma_f32_16x16x32_bf16 v[16:19], v[116:119], v[108:111], v[16:19]
	v_mfma_f32_16x16x32_bf16 v[20:23], v[120:123], v[108:111], v[20:23]
	v_mfma_f32_16x16x32_bf16 v[24:27], v[124:127], v[108:111], v[24:27]
	v_mfma_f32_16x16x32_bf16 v[28:31], v[128:131], v[108:111], v[28:31]
	v_mfma_f32_16x16x32_bf16 v[48:51], v[116:119], v[112:115], v[48:51]
	v_mfma_f32_16x16x32_bf16 v[52:55], v[120:123], v[112:115], v[52:55]
	v_mfma_f32_16x16x32_bf16 v[56:59], v[124:127], v[112:115], v[56:59]
	v_mfma_f32_16x16x32_bf16 v[60:63], v[128:131], v[112:115], v[60:63]
	ds_read_b128 v[108:111], v73 offset:0
	ds_read_b128 v[112:115], v73 offset:8192
	ds_read_b128 v[116:119], v77 offset:0
	ds_read_b128 v[120:123], v77 offset:8192
	ds_read_b128 v[124:127], v77 offset:16384
	ds_read_b128 v[128:131], v77 offset:24576
	s_waitcnt lgkmcnt(6)
	v_mfma_f32_16x16x32_bf16 v[16:19], v[92:95], v[84:87], v[16:19]
	v_mfma_f32_16x16x32_bf16 v[20:23], v[96:99], v[84:87], v[20:23]
	v_mfma_f32_16x16x32_bf16 v[24:27], v[100:103], v[84:87], v[24:27]
	v_mfma_f32_16x16x32_bf16 v[28:31], v[104:107], v[84:87], v[28:31]
	v_mfma_f32_16x16x32_bf16 v[48:51], v[92:95], v[88:91], v[48:51]
	v_mfma_f32_16x16x32_bf16 v[52:55], v[96:99], v[88:91], v[52:55]
	v_mfma_f32_16x16x32_bf16 v[56:59], v[100:103], v[88:91], v[56:59]
	v_mfma_f32_16x16x32_bf16 v[60:63], v[104:107], v[88:91], v[60:63]
	ds_read_b128 v[84:87], v70 offset:256
	ds_read_b128 v[88:91], v70 offset:8448
	ds_read_b128 v[92:95], v74 offset:256
	ds_read_b128 v[96:99], v74 offset:8448
	ds_read_b128 v[100:103], v74 offset:16640
	ds_read_b128 v[104:107], v74 offset:24832
	s_waitcnt lgkmcnt(6)
	v_mfma_f32_16x16x32_bf16 v[16:19], v[116:119], v[108:111], v[16:19]
	v_mfma_f32_16x16x32_bf16 v[20:23], v[120:123], v[108:111], v[20:23]
	v_mfma_f32_16x16x32_bf16 v[24:27], v[124:127], v[108:111], v[24:27]
	v_mfma_f32_16x16x32_bf16 v[28:31], v[128:131], v[108:111], v[28:31]
	v_mfma_f32_16x16x32_bf16 v[48:51], v[116:119], v[112:115], v[48:51]
	v_mfma_f32_16x16x32_bf16 v[52:55], v[120:123], v[112:115], v[52:55]
	v_mfma_f32_16x16x32_bf16 v[56:59], v[124:127], v[112:115], v[56:59]
	v_mfma_f32_16x16x32_bf16 v[60:63], v[128:131], v[112:115], v[60:63]
	ds_read_b128 v[108:111], v71 offset:256
	ds_read_b128 v[112:115], v71 offset:8448
	ds_read_b128 v[116:119], v75 offset:256
	ds_read_b128 v[120:123], v75 offset:8448
	ds_read_b128 v[124:127], v75 offset:16640
	ds_read_b128 v[128:131], v75 offset:24832
	s_waitcnt lgkmcnt(6)
	v_mfma_f32_16x16x32_bf16 v[16:19], v[92:95], v[84:87], v[16:19]
	v_mfma_f32_16x16x32_bf16 v[20:23], v[96:99], v[84:87], v[20:23]
	v_mfma_f32_16x16x32_bf16 v[24:27], v[100:103], v[84:87], v[24:27]
	v_mfma_f32_16x16x32_bf16 v[28:31], v[104:107], v[84:87], v[28:31]
	v_mfma_f32_16x16x32_bf16 v[48:51], v[92:95], v[88:91], v[48:51]
	v_mfma_f32_16x16x32_bf16 v[52:55], v[96:99], v[88:91], v[52:55]
	v_mfma_f32_16x16x32_bf16 v[56:59], v[100:103], v[88:91], v[56:59]
	v_mfma_f32_16x16x32_bf16 v[60:63], v[104:107], v[88:91], v[60:63]
	ds_read_b128 v[84:87], v72 offset:256
	ds_read_b128 v[88:91], v72 offset:8448
	ds_read_b128 v[92:95], v76 offset:256
	ds_read_b128 v[96:99], v76 offset:8448
	ds_read_b128 v[100:103], v76 offset:16640
	ds_read_b128 v[104:107], v76 offset:24832
	s_waitcnt lgkmcnt(6)
	v_mfma_f32_16x16x32_bf16 v[16:19], v[116:119], v[108:111], v[16:19]
	v_mfma_f32_16x16x32_bf16 v[20:23], v[120:123], v[108:111], v[20:23]
	v_mfma_f32_16x16x32_bf16 v[24:27], v[124:127], v[108:111], v[24:27]
	v_mfma_f32_16x16x32_bf16 v[28:31], v[128:131], v[108:111], v[28:31]
	v_mfma_f32_16x16x32_bf16 v[48:51], v[116:119], v[112:115], v[48:51]
	v_mfma_f32_16x16x32_bf16 v[52:55], v[120:123], v[112:115], v[52:55]
	v_mfma_f32_16x16x32_bf16 v[56:59], v[124:127], v[112:115], v[56:59]
	v_mfma_f32_16x16x32_bf16 v[60:63], v[128:131], v[112:115], v[60:63]
	ds_read_b128 v[108:111], v73 offset:256
	ds_read_b128 v[112:115], v73 offset:8448
	ds_read_b128 v[116:119], v77 offset:256
	ds_read_b128 v[120:123], v77 offset:8448
	ds_read_b128 v[124:127], v77 offset:16640
	ds_read_b128 v[128:131], v77 offset:24832
	s_waitcnt lgkmcnt(6)
	v_mfma_f32_16x16x32_bf16 v[16:19], v[92:95], v[84:87], v[16:19]
	v_mfma_f32_16x16x32_bf16 v[20:23], v[96:99], v[84:87], v[20:23]
	v_mfma_f32_16x16x32_bf16 v[24:27], v[100:103], v[84:87], v[24:27]
	v_mfma_f32_16x16x32_bf16 v[28:31], v[104:107], v[84:87], v[28:31]
	v_mfma_f32_16x16x32_bf16 v[48:51], v[92:95], v[88:91], v[48:51]
	v_mfma_f32_16x16x32_bf16 v[52:55], v[96:99], v[88:91], v[52:55]
	v_mfma_f32_16x16x32_bf16 v[56:59], v[100:103], v[88:91], v[56:59]
	v_mfma_f32_16x16x32_bf16 v[60:63], v[104:107], v[88:91], v[60:63]
	s_waitcnt lgkmcnt(0)
	v_mfma_f32_16x16x32_bf16 v[16:19], v[116:119], v[108:111], v[16:19]
	v_mfma_f32_16x16x32_bf16 v[20:23], v[120:123], v[108:111], v[20:23]
	v_mfma_f32_16x16x32_bf16 v[24:27], v[124:127], v[108:111], v[24:27]
	v_mfma_f32_16x16x32_bf16 v[28:31], v[128:131], v[108:111], v[28:31]
	v_mfma_f32_16x16x32_bf16 v[48:51], v[116:119], v[112:115], v[48:51]
	v_mfma_f32_16x16x32_bf16 v[52:55], v[120:123], v[112:115], v[52:55]
	v_mfma_f32_16x16x32_bf16 v[56:59], v[124:127], v[112:115], v[56:59]
	v_mfma_f32_16x16x32_bf16 v[60:63], v[128:131], v[112:115], v[60:63]
	s_nop 7
	global_store_dwordx4 v69, v[0:3], s[18:19] offset:0
	global_store_dwordx4 v69, v[4:7], s[18:19] offset:64
	global_store_dwordx4 v69, v[8:11], s[18:19] offset:128
	global_store_dwordx4 v69, v[12:15], s[18:19] offset:192
	global_store_dwordx4 v69, v[16:19], s[18:19] offset:512
	global_store_dwordx4 v69, v[20:23], s[18:19] offset:576
	global_store_dwordx4 v69, v[24:27], s[18:19] offset:640
	global_store_dwordx4 v69, v[28:31], s[18:19] offset:704
	global_store_dwordx4 v69, v[32:35], s[42:43] offset:0
	global_store_dwordx4 v69, v[36:39], s[42:43] offset:64
	global_store_dwordx4 v69, v[40:43], s[42:43] offset:128
	global_store_dwordx4 v69, v[44:47], s[42:43] offset:192
	global_store_dwordx4 v69, v[48:51], s[42:43] offset:512
	global_store_dwordx4 v69, v[52:55], s[42:43] offset:576
	global_store_dwordx4 v69, v[56:59], s[42:43] offset:640
	global_store_dwordx4 v69, v[60:63], s[42:43] offset:704
	s_barrier
.Lmain_14:
	v_lshlrev_b32_e32 v0, 4, v231
	v_and_b32_e32 v2, 4, v237
	v_and_b32_e32 v137, 24, v238
	s_movk_i32 s6, 0x70
	v_bitop3_b32 v8, v0, v239, 48 bitop3:0x6c
	v_or3_b32 v2, v2, v235, v137
	v_and_or_b32 v3, v236, s6, v234
	s_movk_i32 s6, 0x60
	v_add_u32_e32 v9, 0x2000, v0
	v_or_b32_e32 v1, v8, v139
	v_and_or_b32 v4, v236, s6, v2
	v_lshrrev_b32_e32 v0, 7, v9
	s_movk_i32 s6, 0xf0
	v_lshl_or_b32 v128, v3, 12, v1
	v_and_or_b32 v3, v0, s6, v234
	s_movk_i32 s6, 0xe0
	s_add_u32 s3, s28, 0x7800000
	v_and_or_b32 v0, v0, s6, v2
	s_addc_u32 s62, s29, 0
	v_lshl_or_b32 v130, v4, 12, v1
	v_lshl_or_b32 v132, v3, 12, v1
	v_lshl_or_b32 v134, v0, 12, v1
	v_lshlrev_b32_e32 v153, 1, v137
	v_and_b32_e32 v0, 0x3c0, v233
	v_and_b32_e32 v1, 32, v138
	s_ashr_i32 s63, s34, 31
	s_ashr_i32 s64, s2, 31
	v_mov_b32_e32 v131, 0
	v_bitop3_b32 v152, v153, v1, v0 bitop3:0x36
	s_cmpk_gt_i32 s2, 0xff
	v_mov_b32_e32 v135, v131
	v_mov_b32_e32 v129, v131
	v_mov_b32_e32 v133, v131
	v_readfirstlane_b32 s7, v231
	s_cbranch_scc1 .LBB0_2133
	s_add_u32 s17, s28, 0x19a00000
	s_addc_u32 s36, s29, 0
	s_lshr_b32 s6, s64, 29
	s_add_i32 s6, s2, s6
	s_and_b32 s10, s6, -8
	s_lshr_b32 s15, s7, 6
	s_sub_i32 s10, s2, s10
	s_lshr_b32 s14, s7, 8
	s_lshl_b32 s37, s15, 10
	s_lshl_b32 s12, s10, 5
	s_ashr_i32 s6, s6, 3
	s_mul_i32 s11, s10, 33
	s_cmp_lt_i32 s10, 0
	s_cselect_b32 s10, s11, s12
	s_add_i32 s6, s10, s6
	s_ashr_i32 s10, s6, 31
	s_lshr_b32 s10, s10, 26
	s_add_i32 s10, s6, s10
	s_ashr_i32 s11, s10, 6
	s_andn2_b32 s10, s10, 63
	s_sub_i32 s10, s6, s10
	s_bfe_i32 s6, s10, 0x80000
	s_bfe_u32 s6, s6, 0x3000c
	s_add_i32 s12, s10, s6
	s_bfe_i32 s6, s12, 0x80000
	s_and_b32 s12, s12, 0xf8
	s_sub_i32 s10, s10, s12
	s_lshl_b32 s11, s11, 3
	s_sext_i32_i8 s10, s10
	s_add_i32 s12, s11, s10
	s_sext_i32_i16 s6, s6
	s_ashr_i32 s13, s12, 31
	s_lshr_b32 s6, s6, 3
	s_lshl_b64 s[10:11], s[12:13], 20
	s_add_u32 s22, s17, s10
	s_addc_u32 s23, s36, s11
	s_bfe_i64 s[10:11], s[6:7], 0x100000
	s_lshl_b64 s[10:11], s[10:11], 20
	s_add_u32 s24, s3, s10
	s_addc_u32 s25, s62, s11
	s_add_i32 s38, s37, 0
	s_add_i32 m0, s38, 0x10000
	v_lshl_add_u64 v[0:1], s[24:25], 0, v[130:131]
	global_load_lds_dwordx4 v[0:1], off
	s_add_i32 m0, s38, 0x12000
	s_add_u32 s10, s24, 0x80000
	v_lshl_add_u64 v[2:3], s[24:25], 0, v[134:135]
	s_addc_u32 s11, s25, 0
	global_load_lds_dwordx4 v[2:3], off
	s_add_i32 m0, s38, 0x14000
	v_lshl_add_u64 v[4:5], s[10:11], 0, v[130:131]
	global_load_lds_dwordx4 v[4:5], off
	v_lshl_add_u64 v[4:5], s[10:11], 0, v[134:135]
	s_add_i32 m0, s38, 0x16000
	s_add_i32 s39, s38, 0x2000
	global_load_lds_dwordx4 v[4:5], off
	v_lshl_add_u64 v[6:7], s[22:23], 0, v[128:129]
	s_mov_b32 m0, s38
	s_add_u32 s10, s22, 0x80000
	global_load_lds_dwordx4 v[6:7], off
	v_lshl_add_u64 v[4:5], s[22:23], 0, v[132:133]
	s_mov_b32 m0, s39
	s_addc_u32 s11, s23, 0
	s_add_i32 s40, s38, 0x4000
	global_load_lds_dwordx4 v[4:5], off
	v_lshl_add_u64 v[10:11], s[10:11], 0, v[128:129]
	s_mov_b32 m0, s40
	s_add_i32 s41, s38, 0x6000
	global_load_lds_dwordx4 v[10:11], off
	v_lshl_add_u64 v[10:11], s[10:11], 0, v[132:133]
	s_mov_b32 m0, s41
	s_cmp_eq_u32 s14, 1
	global_load_lds_dwordx4 v[10:11], off
	s_cselect_b64 s[10:11], -1, 0
	s_cmp_lg_u32 s14, 1
	s_mov_b32 s42, 0
	s_cbranch_scc1 .LBB0_2116
	s_barrier

.LBB0_2133:
	s_cmp_gt_i32 s2, 63
	v_readfirstlane_b32 s10, v231
.LBB0_2149:
	s_cmp_gt_i32 s31, 15
	s_cselect_b64 s[6:7], -1, 0
	s_and_b64 s[8:9], s[8:9], s[6:7]
	s_andn2_b64 vcc, exec, s[8:9]
	s_cbranch_vccnz .LBB0_2203
	s_waitcnt vmcnt(0)
	s_waitcnt vmcnt(0) lgkmcnt(0)
	s_barrier
	s_and_saveexec_b64 s[8:9], s[4:5]
	s_cbranch_execz .LBB0_2202
	s_add_i32 s3, 0, 0x20000
	v_mov_b32_e32 v0, s3
	s_waitcnt vmcnt(0) expcnt(0) lgkmcnt(0)
	ds_read_b32 v2, v0
	s_add_i32 s3, 0, 0x20004
	v_mov_b32_e32 v0, s3
	ds_read_b32 v0, v0
	s_waitcnt lgkmcnt(1)
	v_cmp_ne_u32_e32 vcc, 0, v2
	s_cbranch_vccnz .LBB0_2166
	s_add_u32 s10, s28, 0x30300200
	s_addc_u32 s11, s29, 0
	s_add_u32 s12, s28, 0x30300400
	s_addc_u32 s13, s29, 0
	s_add_u32 s14, s28, 0x30300500
	s_addc_u32 s15, s29, 0
	s_add_u32 s16, s28, 0x30300600
	s_addc_u32 s17, s29, 0
	s_add_u32 s18, s28, 0x30300700
	s_addc_u32 s19, s29, 0
	s_add_u32 s20, s28, 0x30300800
	s_addc_u32 s21, s29, 0
	s_add_u32 s22, s28, 0x30300900
	s_addc_u32 s23, s29, 0
	s_add_u32 s24, s28, 0x30300a00
	s_addc_u32 s25, s29, 0
	s_add_u32 s26, s28, 0x30300b00
	s_addc_u32 s27, s29, 0
	s_add_u32 s36, s28, 0x30300c00
	s_addc_u32 s37, s29, 0
	s_add_u32 s38, s28, 0x30300d00
	s_addc_u32 s39, s29, 0
	s_add_u32 s40, s28, 0x30300e00
	s_addc_u32 s41, s29, 0
	s_add_u32 s42, s28, 0x30300f00
	s_addc_u32 s43, s29, 0
	s_add_u32 s44, s28, 0x30301000
	s_addc_u32 s45, s29, 0
	s_add_u32 s46, s28, 0x30301100
	s_addc_u32 s47, s29, 0
	s_add_u32 s58, s28, 0x30301200
	s_addc_u32 s59, s29, 0
	s_mul_i32 s3, s35, s82
	s_add_u32 s60, s28, 0x30301300
	s_mul_i32 s3, s3, s34
	s_addc_u32 s61, s29, 0
	s_mov_b32 s68, 1
	v_mov_b32_e32 v16, 0
	s_branch .LBB0_2154

.LBB0_2362:
	s_cmp_lt_i32 s30, 18
	s_cselect_b64 s[8:9], -1, 0
	s_and_b64 s[8:9], s[8:9], s[6:7]
	s_andn2_b64 vcc, exec, s[8:9]
	s_cbranch_vccnz .LBB0_2399
	s_cmpk_gt_i32 s2, 0xaf
	s_cbranch_scc1 .Lmain_17
	v_and_b32_e32 v64, 63, v231
	v_and_b32_e32 v65, 15, v64
	v_bfe_u32 v66, v64, 4, 2
	v_readfirstlane_b32 s44, v230
	s_and_b32 s60, s2, 7
	s_lshr_b32 s61, s2, 3
	s_lshl_b32 s63, s61, 9
	s_nop 0
	s_and_b32 s40, s44, 3
	s_lshr_b32 s59, s44, 2
	v_and_b32_e32 v67, 3, v65
	v_xor_b32_e32 v67, v66, v67
	v_lshlrev_b32_e32 v67, 4, v67
	v_lshl_add_u32 v67, v65, 9, v67
	v_lshrrev_b32_e32 v69, 2, v65
	s_lshl_b32 s64, s40, 14
	s_lshl_b32 s76, s59, 15
	s_add_u32 s76, s76, 0x10000
	v_xor_b32_e32 v70, 0, v69
	v_lshl_add_u32 v70, v70, 6, v67
	v_add_u32_e32 v74, s76, v70
	v_add_u32_e32 v70, s64, v70
	v_xor_b32_e32 v71, 1, v69
	v_lshl_add_u32 v71, v71, 6, v67
	v_add_u32_e32 v75, s76, v71
	v_add_u32_e32 v71, s64, v71
	v_xor_b32_e32 v72, 2, v69
	v_lshl_add_u32 v72, v72, 6, v67
	v_add_u32_e32 v76, s76, v72
	v_add_u32_e32 v72, s64, v72
	v_xor_b32_e32 v73, 3, v69
	v_lshl_add_u32 v73, v73, 6, v67
	v_add_u32_e32 v77, s76, v73
	v_add_u32_e32 v73, s64, v73
	v_lshrrev_b32_e32 v68, 5, v64
	s_lshl_b32 s77, s44, 1
	v_add_u32_e32 v69, s77, v68
	v_and_b32_e32 v67, 31, v64
	v_xor_b32_e32 v67, v67, v69
	v_lshlrev_b32_e32 v67, 4, v67
	v_mul_u32_u24_e32 v68, 0x2c00, v68
	v_add_u32_e32 v68, v68, v67
	v_lshlrev_b32_e32 v69, 13, v65
	v_lshl_add_u32 v69, v66, 4, v69
	s_lshl_b32 s62, s44, 1
	s_mul_i32 s62, s62, 0x2c00
	s_add_u32 s14, s28, 0x1d300000
	s_addc_u32 s15, s29, 0
	s_add_u32 s14, s14, 0x5800000
	s_addc_u32 s15, s15, 0
	s_add_u32 s14, s14, s62
	s_addc_u32 s15, s15, 0
	s_add_u32 s14, s14, s63
	s_addc_u32 s15, s15, 0
	s_lshl_b32 s64, s60, 8
	s_mul_i32 s64, s64, 0x2c00
	s_add_u32 s16, s28, 0xac00000
	s_addc_u32 s17, s29, 0
	s_add_u32 s16, s16, s64
	s_addc_u32 s17, s17, 0
	s_add_u32 s16, s16, s62
	s_addc_u32 s17, s17, 0
	s_add_u32 s16, s16, s63
	s_addc_u32 s17, s17, 0
	s_lshl_b32 s76, s61, 7
	s_lshl_b32 s77, s40, 5
	s_add_u32 s76, s76, s77
	s_lshl_b32 s76, s76, 13
	s_lshl_b32 s77, s60, 10
	s_lshl_b32 s3, s59, 8
	s_add_u32 s76, s76, s77
	s_add_u32 s76, s76, s3
	s_add_u32 s18, s28, 0x2ec00000
	s_addc_u32 s19, s29, 0
	s_add_u32 s18, s18, s76
	s_addc_u32 s19, s19, 0
	s_add_u32 s42, s18, 0x20000
	s_addc_u32 s43, s19, 0
	s_lshl_b32 s62, s44, 10
	s_mov_b64 s[12:13], s[14:15]
	s_add_u32 s11, s62, 0x0
	s_mov_b32 m0, s11
	s_add_u32 s11, s11, 0x2000
	global_load_lds_dwordx4 v68, s[12:13]
	s_add_u32 s12, s12, 0x2c000
	s_addc_u32 s13, s13, 0
	s_mov_b32 m0, s11
	s_add_u32 s11, s11, 0x2000
	global_load_lds_dwordx4 v68, s[12:13]
	s_add_u32 s12, s12, 0x2c000
	s_addc_u32 s13, s13, 0
	s_mov_b32 m0, s11
	s_add_u32 s11, s11, 0x2000
	global_load_lds_dwordx4 v68, s[12:13]
	s_add_u32 s12, s12, 0x2c000
	s_addc_u32 s13, s13, 0
	s_mov_b32 m0, s11
	s_add_u32 s11, s11, 0x2000
	global_load_lds_dwordx4 v68, s[12:13]
	s_add_u32 s12, s12, 0x2c000
	s_addc_u32 s13, s13, 0
	s_mov_b32 m0, s11
	s_add_u32 s11, s11, 0x2000
	global_load_lds_dwordx4 v68, s[12:13]
	s_add_u32 s12, s12, 0x2c000
	s_addc_u32 s13, s13, 0
	s_mov_b32 m0, s11
	s_add_u32 s11, s11, 0x2000
	global_load_lds_dwordx4 v68, s[12:13]
	s_add_u32 s12, s12, 0x2c000
	s_addc_u32 s13, s13, 0
	s_mov_b32 m0, s11
	s_add_u32 s11, s11, 0x2000
	global_load_lds_dwordx4 v68, s[12:13]
	s_add_u32 s12, s12, 0x2c000
	s_addc_u32 s13, s13, 0
	s_mov_b32 m0, s11
	s_add_u32 s11, s11, 0x2000
	global_load_lds_dwordx4 v68, s[12:13]
	s_add_u32 s12, s12, 0x2c000
	s_addc_u32 s13, s13, 0
	s_mov_b64 s[12:13], s[16:17]
	s_add_u32 s11, s62, 0x10000
	s_mov_b32 m0, s11
	s_add_u32 s11, s11, 0x2000
	global_load_lds_dwordx4 v68, s[12:13]
	s_add_u32 s12, s12, 0x2c000
	s_addc_u32 s13, s13, 0
	s_mov_b32 m0, s11
	s_add_u32 s11, s11, 0x2000
	global_load_lds_dwordx4 v68, s[12:13]
	s_add_u32 s12, s12, 0x2c000
	s_addc_u32 s13, s13, 0
	s_mov_b32 m0, s11
	s_add_u32 s11, s11, 0x2000
	global_load_lds_dwordx4 v68, s[12:13]
	s_add_u32 s12, s12, 0x2c000
	s_addc_u32 s13, s13, 0
	s_mov_b32 m0, s11
	s_add_u32 s11, s11, 0x2000
	global_load_lds_dwordx4 v68, s[12:13]
	s_add_u32 s12, s12, 0x2c000
	s_addc_u32 s13, s13, 0
	s_mov_b32 m0, s11
	s_add_u32 s11, s11, 0x2000
	global_load_lds_dwordx4 v68, s[12:13]
	s_add_u32 s12, s12, 0x2c000
	s_addc_u32 s13, s13, 0
	s_mov_b32 m0, s11
	s_add_u32 s11, s11, 0x2000
	global_load_lds_dwordx4 v68, s[12:13]
	s_add_u32 s12, s12, 0x2c000
	s_addc_u32 s13, s13, 0
	s_mov_b32 m0, s11
	s_add_u32 s11, s11, 0x2000
	global_load_lds_dwordx4 v68, s[12:13]
	s_add_u32 s12, s12, 0x2c000
	s_addc_u32 s13, s13, 0
	s_mov_b32 m0, s11
	s_add_u32 s11, s11, 0x2000
	global_load_lds_dwordx4 v68, s[12:13]
	s_add_u32 s12, s12, 0x2c000
	s_addc_u32 s13, s13, 0
	s_add_u32 s16, s16, 0x160000
	s_addc_u32 s17, s17, 0
	s_waitcnt vmcnt(0)
	s_barrier
	ds_read_b128 v[84:87], v70 offset:0
	ds_read_b128 v[88:91], v70 offset:8192
	ds_read_b128 v[92:95], v74 offset:0
	ds_read_b128 v[96:99], v74 offset:8192
	ds_read_b128 v[100:103], v74 offset:16384
	ds_read_b128 v[104:107], v74 offset:24576
	ds_read_b128 v[108:111], v71 offset:0
	ds_read_b128 v[112:115], v71 offset:8192
	ds_read_b128 v[116:119], v75 offset:0
	ds_read_b128 v[120:123], v75 offset:8192
	ds_read_b128 v[124:127], v75 offset:16384
	ds_read_b128 v[128:131], v75 offset:24576
	s_waitcnt lgkmcnt(6)
	v_mfma_f32_16x16x32_bf16 v[0:3], v[92:95], v[84:87], 0
	v_mfma_f32_16x16x32_bf16 v[4:7], v[96:99], v[84:87], 0
	v_mfma_f32_16x16x32_bf16 v[8:11], v[100:103], v[84:87], 0
	v_mfma_f32_16x16x32_bf16 v[12:15], v[104:107], v[84:87], 0
	v_mfma_f32_16x16x32_bf16 v[32:35], v[92:95], v[88:91], 0
	v_mfma_f32_16x16x32_bf16 v[36:39], v[96:99], v[88:91], 0
	v_mfma_f32_16x16x32_bf16 v[40:43], v[100:103], v[88:91], 0
	v_mfma_f32_16x16x32_bf16 v[44:47], v[104:107], v[88:91], 0
	ds_read_b128 v[84:87], v72 offset:0
	ds_read_b128 v[88:91], v72 offset:8192
	ds_read_b128 v[92:95], v76 offset:0
	ds_read_b128 v[96:99], v76 offset:8192
	ds_read_b128 v[100:103], v76 offset:16384
	ds_read_b128 v[104:107], v76 offset:24576
	s_waitcnt lgkmcnt(6)
	v_mfma_f32_16x16x32_bf16 v[0:3], v[116:119], v[108:111], v[0:3]
	v_mfma_f32_16x16x32_bf16 v[4:7], v[120:123], v[108:111], v[4:7]
	v_mfma_f32_16x16x32_bf16 v[8:11], v[124:127], v[108:111], v[8:11]
	v_mfma_f32_16x16x32_bf16 v[12:15], v[128:131], v[108:111], v[12:15]
	v_mfma_f32_16x16x32_bf16 v[32:35], v[116:119], v[112:115], v[32:35]
	v_mfma_f32_16x16x32_bf16 v[36:39], v[120:123], v[112:115], v[36:39]
	v_mfma_f32_16x16x32_bf16 v[40:43], v[124:127], v[112:115], v[40:43]
	v_mfma_f32_16x16x32_bf16 v[44:47], v[128:131], v[112:115], v[44:47]
	ds_read_b128 v[108:111], v73 offset:0
	ds_read_b128 v[112:115], v73 offset:8192
	ds_read_b128 v[116:119], v77 offset:0
	ds_read_b128 v[120:123], v77 offset:8192
	ds_read_b128 v[124:127], v77 offset:16384
	ds_read_b128 v[128:131], v77 offset:24576
	s_waitcnt lgkmcnt(6)
	v_mfma_f32_16x16x32_bf16 v[0:3], v[92:95], v[84:87], v[0:3]
	v_mfma_f32_16x16x32_bf16 v[4:7], v[96:99], v[84:87], v[4:7]
	v_mfma_f32_16x16x32_bf16 v[8:11], v[100:103], v[84:87], v[8:11]
	v_mfma_f32_16x16x32_bf16 v[12:15], v[104:107], v[84:87], v[12:15]
	v_mfma_f32_16x16x32_bf16 v[32:35], v[92:95], v[88:91], v[32:35]
	v_mfma_f32_16x16x32_bf16 v[36:39], v[96:99], v[88:91], v[36:39]
	v_mfma_f32_16x16x32_bf16 v[40:43], v[100:103], v[88:91], v[40:43]
	v_mfma_f32_16x16x32_bf16 v[44:47], v[104:107], v[88:91], v[44:47]
	ds_read_b128 v[84:87], v70 offset:256
	ds_read_b128 v[88:91], v70 offset:8448
	ds_read_b128 v[92:95], v74 offset:256
	ds_read_b128 v[96:99], v74 offset:8448
	ds_read_b128 v[100:103], v74 offset:16640
	ds_read_b128 v[104:107], v74 offset:24832
	s_waitcnt lgkmcnt(6)
	v_mfma_f32_16x16x32_bf16 v[0:3], v[116:119], v[108:111], v[0:3]
	v_mfma_f32_16x16x32_bf16 v[4:7], v[120:123], v[108:111], v[4:7]
	v_mfma_f32_16x16x32_bf16 v[8:11], v[124:127], v[108:111], v[8:11]
	v_mfma_f32_16x16x32_bf16 v[12:15], v[128:131], v[108:111], v[12:15]
	v_mfma_f32_16x16x32_bf16 v[32:35], v[116:119], v[112:115], v[32:35]
	v_mfma_f32_16x16x32_bf16 v[36:39], v[120:123], v[112:115], v[36:39]
	v_mfma_f32_16x16x32_bf16 v[40:43], v[124:127], v[112:115], v[40:43]
	v_mfma_f32_16x16x32_bf16 v[44:47], v[128:131], v[112:115], v[44:47]
	ds_read_b128 v[108:111], v71 offset:256
	ds_read_b128 v[112:115], v71 offset:8448
	ds_read_b128 v[116:119], v75 offset:256
	ds_read_b128 v[120:123], v75 offset:8448
	ds_read_b128 v[124:127], v75 offset:16640
	ds_read_b128 v[128:131], v75 offset:24832
	s_waitcnt lgkmcnt(6)
	v_mfma_f32_16x16x32_bf16 v[0:3], v[92:95], v[84:87], v[0:3]
	v_mfma_f32_16x16x32_bf16 v[4:7], v[96:99], v[84:87], v[4:7]
	v_mfma_f32_16x16x32_bf16 v[8:11], v[100:103], v[84:87], v[8:11]
	v_mfma_f32_16x16x32_bf16 v[12:15], v[104:107], v[84:87], v[12:15]
	v_mfma_f32_16x16x32_bf16 v[32:35], v[92:95], v[88:91], v[32:35]
	v_mfma_f32_16x16x32_bf16 v[36:39], v[96:99], v[88:91], v[36:39]
	v_mfma_f32_16x16x32_bf16 v[40:43], v[100:103], v[88:91], v[40:43]
	v_mfma_f32_16x16x32_bf16 v[44:47], v[104:107], v[88:91], v[44:47]
	ds_read_b128 v[84:87], v72 offset:256
	ds_read_b128 v[88:91], v72 offset:8448
	ds_read_b128 v[92:95], v76 offset:256
	ds_read_b128 v[96:99], v76 offset:8448
	ds_read_b128 v[100:103], v76 offset:16640
	ds_read_b128 v[104:107], v76 offset:24832
	s_waitcnt lgkmcnt(6)
	v_mfma_f32_16x16x32_bf16 v[0:3], v[116:119], v[108:111], v[0:3]
	v_mfma_f32_16x16x32_bf16 v[4:7], v[120:123], v[108:111], v[4:7]
	v_mfma_f32_16x16x32_bf16 v[8:11], v[124:127], v[108:111], v[8:11]
	v_mfma_f32_16x16x32_bf16 v[12:15], v[128:131], v[108:111], v[12:15]
	v_mfma_f32_16x16x32_bf16 v[32:35], v[116:119], v[112:115], v[32:35]
	v_mfma_f32_16x16x32_bf16 v[36:39], v[120:123], v[112:115], v[36:39]
	v_mfma_f32_16x16x32_bf16 v[40:43], v[124:127], v[112:115], v[40:43]
	v_mfma_f32_16x16x32_bf16 v[44:47], v[128:131], v[112:115], v[44:47]
	ds_read_b128 v[108:111], v73 offset:256
	ds_read_b128 v[112:115], v73 offset:8448
	ds_read_b128 v[116:119], v77 offset:256
	ds_read_b128 v[120:123], v77 offset:8448
	ds_read_b128 v[124:127], v77 offset:16640
	ds_read_b128 v[128:131], v77 offset:24832
	s_waitcnt lgkmcnt(6)
	v_mfma_f32_16x16x32_bf16 v[0:3], v[92:95], v[84:87], v[0:3]
	v_mfma_f32_16x16x32_bf16 v[4:7], v[96:99], v[84:87], v[4:7]
	v_mfma_f32_16x16x32_bf16 v[8:11], v[100:103], v[84:87], v[8:11]
	v_mfma_f32_16x16x32_bf16 v[12:15], v[104:107], v[84:87], v[12:15]
	v_mfma_f32_16x16x32_bf16 v[32:35], v[92:95], v[88:91], v[32:35]
	v_mfma_f32_16x16x32_bf16 v[36:39], v[96:99], v[88:91], v[36:39]
	v_mfma_f32_16x16x32_bf16 v[40:43], v[100:103], v[88:91], v[40:43]
	v_mfma_f32_16x16x32_bf16 v[44:47], v[104:107], v[88:91], v[44:47]
	s_waitcnt lgkmcnt(0)
	v_mfma_f32_16x16x32_bf16 v[0:3], v[116:119], v[108:111], v[0:3]
	v_mfma_f32_16x16x32_bf16 v[4:7], v[120:123], v[108:111], v[4:7]
	v_mfma_f32_16x16x32_bf16 v[8:11], v[124:127], v[108:111], v[8:11]
	v_mfma_f32_16x16x32_bf16 v[12:15], v[128:131], v[108:111], v[12:15]
	v_mfma_f32_16x16x32_bf16 v[32:35], v[116:119], v[112:115], v[32:35]
	v_mfma_f32_16x16x32_bf16 v[36:39], v[120:123], v[112:115], v[36:39]
	v_mfma_f32_16x16x32_bf16 v[40:43], v[124:127], v[112:115], v[40:43]
	v_mfma_f32_16x16x32_bf16 v[44:47], v[128:131], v[112:115], v[44:47]
	s_barrier
	s_mov_b64 s[12:13], s[16:17]
	s_add_u32 s11, s62, 0x10000
	s_mov_b32 m0, s11
	s_add_u32 s11, s11, 0x2000
	global_load_lds_dwordx4 v68, s[12:13]
	s_add_u32 s12, s12, 0x2c000
	s_addc_u32 s13, s13, 0
	s_mov_b32 m0, s11
	s_add_u32 s11, s11, 0x2000
	global_load_lds_dwordx4 v68, s[12:13]
	s_add_u32 s12, s12, 0x2c000
	s_addc_u32 s13, s13, 0
	s_mov_b32 m0, s11
	s_add_u32 s11, s11, 0x2000
	global_load_lds_dwordx4 v68, s[12:13]
	s_add_u32 s12, s12, 0x2c000
	s_addc_u32 s13, s13, 0
	s_mov_b32 m0, s11
	s_add_u32 s11, s11, 0x2000
	global_load_lds_dwordx4 v68, s[12:13]
	s_add_u32 s12, s12, 0x2c000
	s_addc_u32 s13, s13, 0
	s_mov_b32 m0, s11
	s_add_u32 s11, s11, 0x2000
	global_load_lds_dwordx4 v68, s[12:13]
	s_add_u32 s12, s12, 0x2c000
	s_addc_u32 s13, s13, 0
	s_mov_b32 m0, s11
	s_add_u32 s11, s11, 0x2000
	global_load_lds_dwordx4 v68, s[12:13]
	s_add_u32 s12, s12, 0x2c000
	s_addc_u32 s13, s13, 0
	s_mov_b32 m0, s11
	s_add_u32 s11, s11, 0x2000
	global_load_lds_dwordx4 v68, s[12:13]
	s_add_u32 s12, s12, 0x2c000
	s_addc_u32 s13, s13, 0
	s_mov_b32 m0, s11
	s_add_u32 s11, s11, 0x2000
	global_load_lds_dwordx4 v68, s[12:13]
	s_add_u32 s12, s12, 0x2c000
	s_addc_u32 s13, s13, 0
	s_waitcnt vmcnt(0)
	s_barrier
	ds_read_b128 v[84:87], v70 offset:0
	ds_read_b128 v[88:91], v70 offset:8192
	ds_read_b128 v[92:95], v74 offset:0
	ds_read_b128 v[96:99], v74 offset:8192
	ds_read_b128 v[100:103], v74 offset:16384
	ds_read_b128 v[104:107], v74 offset:24576
	ds_read_b128 v[108:111], v71 offset:0
	ds_read_b128 v[112:115], v71 offset:8192
	ds_read_b128 v[116:119], v75 offset:0
	ds_read_b128 v[120:123], v75 offset:8192
	ds_read_b128 v[124:127], v75 offset:16384
	ds_read_b128 v[128:131], v75 offset:24576
	s_waitcnt lgkmcnt(6)
	v_mfma_f32_16x16x32_bf16 v[16:19], v[92:95], v[84:87], 0
	v_mfma_f32_16x16x32_bf16 v[20:23], v[96:99], v[84:87], 0
	v_mfma_f32_16x16x32_bf16 v[24:27], v[100:103], v[84:87], 0
	v_mfma_f32_16x16x32_bf16 v[28:31], v[104:107], v[84:87], 0
	v_mfma_f32_16x16x32_bf16 v[48:51], v[92:95], v[88:91], 0
	v_mfma_f32_16x16x32_bf16 v[52:55], v[96:99], v[88:91], 0
	v_mfma_f32_16x16x32_bf16 v[56:59], v[100:103], v[88:91], 0
	v_mfma_f32_16x16x32_bf16 v[60:63], v[104:107], v[88:91], 0
	ds_read_b128 v[84:87], v72 offset:0
	ds_read_b128 v[88:91], v72 offset:8192
	ds_read_b128 v[92:95], v76 offset:0
	ds_read_b128 v[96:99], v76 offset:8192
	ds_read_b128 v[100:103], v76 offset:16384
	ds_read_b128 v[104:107], v76 offset:24576
	s_waitcnt lgkmcnt(6)
	v_mfma_f32_16x16x32_bf16 v[16:19], v[116:119], v[108:111], v[16:19]
	v_mfma_f32_16x16x32_bf16 v[20:23], v[120:123], v[108:111], v[20:23]
	v_mfma_f32_16x16x32_bf16 v[24:27], v[124:127], v[108:111], v[24:27]
	v_mfma_f32_16x16x32_bf16 v[28:31], v[128:131], v[108:111], v[28:31]
	v_mfma_f32_16x16x32_bf16 v[48:51], v[116:119], v[112:115], v[48:51]
	v_mfma_f32_16x16x32_bf16 v[52:55], v[120:123], v[112:115], v[52:55]
	v_mfma_f32_16x16x32_bf16 v[56:59], v[124:127], v[112:115], v[56:59]
	v_mfma_f32_16x16x32_bf16 v[60:63], v[128:131], v[112:115], v[60:63]
	ds_read_b128 v[108:111], v73 offset:0
	ds_read_b128 v[112:115], v73 offset:8192
	ds_read_b128 v[116:119], v77 offset:0
	ds_read_b128 v[120:123], v77 offset:8192
	ds_read_b128 v[124:127], v77 offset:16384
	ds_read_b128 v[128:131], v77 offset:24576
	s_waitcnt lgkmcnt(6)
	v_mfma_f32_16x16x32_bf16 v[16:19], v[92:95], v[84:87], v[16:19]
	v_mfma_f32_16x16x32_bf16 v[20:23], v[96:99], v[84:87], v[20:23]
	v_mfma_f32_16x16x32_bf16 v[24:27], v[100:103], v[84:87], v[24:27]
	v_mfma_f32_16x16x32_bf16 v[28:31], v[104:107], v[84:87], v[28:31]
	v_mfma_f32_16x16x32_bf16 v[48:51], v[92:95], v[88:91], v[48:51]
	v_mfma_f32_16x16x32_bf16 v[52:55], v[96:99], v[88:91], v[52:55]
	v_mfma_f32_16x16x32_bf16 v[56:59], v[100:103], v[88:91], v[56:59]
	v_mfma_f32_16x16x32_bf16 v[60:63], v[104:107], v[88:91], v[60:63]
	ds_read_b128 v[84:87], v70 offset:256
	ds_read_b128 v[88:91], v70 offset:8448
	ds_read_b128 v[92:95], v74 offset:256
	ds_read_b128 v[96:99], v74 offset:8448
	ds_read_b128 v[100:103], v74 offset:16640
	ds_read_b128 v[104:107], v74 offset:24832
	s_waitcnt lgkmcnt(6)
	v_mfma_f32_16x16x32_bf16 v[16:19], v[116:119], v[108:111], v[16:19]
	v_mfma_f32_16x16x32_bf16 v[20:23], v[120:123], v[108:111], v[20:23]
	v_mfma_f32_16x16x32_bf16 v[24:27], v[124:127], v[108:111], v[24:27]
	v_mfma_f32_16x16x32_bf16 v[28:31], v[128:131], v[108:111], v[28:31]
	v_mfma_f32_16x16x32_bf16 v[48:51], v[116:119], v[112:115], v[48:51]
	v_mfma_f32_16x16x32_bf16 v[52:55], v[120:123], v[112:115], v[52:55]
	v_mfma_f32_16x16x32_bf16 v[56:59], v[124:127], v[112:115], v[56:59]
	v_mfma_f32_16x16x32_bf16 v[60:63], v[128:131], v[112:115], v[60:63]
	ds_read_b128 v[108:111], v71 offset:256
	ds_read_b128 v[112:115], v71 offset:8448
	ds_read_b128 v[116:119], v75 offset:256
	ds_read_b128 v[120:123], v75 offset:8448
	ds_read_b128 v[124:127], v75 offset:16640
	ds_read_b128 v[128:131], v75 offset:24832
	s_waitcnt lgkmcnt(6)
	v_mfma_f32_16x16x32_bf16 v[16:19], v[92:95], v[84:87], v[16:19]
	v_mfma_f32_16x16x32_bf16 v[20:23], v[96:99], v[84:87], v[20:23]
	v_mfma_f32_16x16x32_bf16 v[24:27], v[100:103], v[84:87], v[24:27]
	v_mfma_f32_16x16x32_bf16 v[28:31], v[104:107], v[84:87], v[28:31]
	v_mfma_f32_16x16x32_bf16 v[48:51], v[92:95], v[88:91], v[48:51]
	v_mfma_f32_16x16x32_bf16 v[52:55], v[96:99], v[88:91], v[52:55]
	v_mfma_f32_16x16x32_bf16 v[56:59], v[100:103], v[88:91], v[56:59]
	v_mfma_f32_16x16x32_bf16 v[60:63], v[104:107], v[88:91], v[60:63]
	ds_read_b128 v[84:87], v72 offset:256
	ds_read_b128 v[88:91], v72 offset:8448
	ds_read_b128 v[92:95], v76 offset:256
	ds_read_b128 v[96:99], v76 offset:8448
	ds_read_b128 v[100:103], v76 offset:16640
	ds_read_b128 v[104:107], v76 offset:24832
	s_waitcnt lgkmcnt(6)
	v_mfma_f32_16x16x32_bf16 v[16:19], v[116:119], v[108:111], v[16:19]
	v_mfma_f32_16x16x32_bf16 v[20:23], v[120:123], v[108:111], v[20:23]
	v_mfma_f32_16x16x32_bf16 v[24:27], v[124:127], v[108:111], v[24:27]
	v_mfma_f32_16x16x32_bf16 v[28:31], v[128:131], v[108:111], v[28:31]
	v_mfma_f32_16x16x32_bf16 v[48:51], v[116:119], v[112:115], v[48:51]
	v_mfma_f32_16x16x32_bf16 v[52:55], v[120:123], v[112:115], v[52:55]
	v_mfma_f32_16x16x32_bf16 v[56:59], v[124:127], v[112:115], v[56:59]
	v_mfma_f32_16x16x32_bf16 v[60:63], v[128:131], v[112:115], v[60:63]
	ds_read_b128 v[108:111], v73 offset:256
	ds_read_b128 v[112:115], v73 offset:8448
	ds_read_b128 v[116:119], v77 offset:256
	ds_read_b128 v[120:123], v77 offset:8448
	ds_read_b128 v[124:127], v77 offset:16640
	ds_read_b128 v[128:131], v77 offset:24832
	s_waitcnt lgkmcnt(6)
	v_mfma_f32_16x16x32_bf16 v[16:19], v[92:95], v[84:87], v[16:19]
	v_mfma_f32_16x16x32_bf16 v[20:23], v[96:99], v[84:87], v[20:23]
	v_mfma_f32_16x16x32_bf16 v[24:27], v[100:103], v[84:87], v[24:27]
	v_mfma_f32_16x16x32_bf16 v[28:31], v[104:107], v[84:87], v[28:31]
	v_mfma_f32_16x16x32_bf16 v[48:51], v[92:95], v[88:91], v[48:51]
	v_mfma_f32_16x16x32_bf16 v[52:55], v[96:99], v[88:91], v[52:55]
	v_mfma_f32_16x16x32_bf16 v[56:59], v[100:103], v[88:91], v[56:59]
	v_mfma_f32_16x16x32_bf16 v[60:63], v[104:107], v[88:91], v[60:63]
	s_waitcnt lgkmcnt(0)
	v_mfma_f32_16x16x32_bf16 v[16:19], v[116:119], v[108:111], v[16:19]
	v_mfma_f32_16x16x32_bf16 v[20:23], v[120:123], v[108:111], v[20:23]
	v_mfma_f32_16x16x32_bf16 v[24:27], v[124:127], v[108:111], v[24:27]
	v_mfma_f32_16x16x32_bf16 v[28:31], v[128:131], v[108:111], v[28:31]
	v_mfma_f32_16x16x32_bf16 v[48:51], v[116:119], v[112:115], v[48:51]
	v_mfma_f32_16x16x32_bf16 v[52:55], v[120:123], v[112:115], v[52:55]
	v_mfma_f32_16x16x32_bf16 v[56:59], v[124:127], v[112:115], v[56:59]
	v_mfma_f32_16x16x32_bf16 v[60:63], v[128:131], v[112:115], v[60:63]
	s_nop 7
	global_store_dwordx4 v69, v[0:3], s[18:19] offset:0
	global_store_dwordx4 v69, v[4:7], s[18:19] offset:64
	global_store_dwordx4 v69, v[8:11], s[18:19] offset:128
	global_store_dwordx4 v69, v[12:15], s[18:19] offset:192
	global_store_dwordx4 v69, v[16:19], s[18:19] offset:512
	global_store_dwordx4 v69, v[20:23], s[18:19] offset:576
	global_store_dwordx4 v69, v[24:27], s[18:19] offset:640
	global_store_dwordx4 v69, v[28:31], s[18:19] offset:704
	global_store_dwordx4 v69, v[32:35], s[42:43] offset:0
	global_store_dwordx4 v69, v[36:39], s[42:43] offset:64
	global_store_dwordx4 v69, v[40:43], s[42:43] offset:128
	global_store_dwordx4 v69, v[44:47], s[42:43] offset:192
	global_store_dwordx4 v69, v[48:51], s[42:43] offset:512
	global_store_dwordx4 v69, v[52:55], s[42:43] offset:576
	global_store_dwordx4 v69, v[56:59], s[42:43] offset:640
	global_store_dwordx4 v69, v[60:63], s[42:43] offset:704
	s_barrier
.Lmain_17:
	v_lshlrev_b32_e32 v0, 4, v231
	v_bitop3_b32 v8, v0, v239, 48 bitop3:0x6c
	s_movk_i32 s6, 0x70
	v_or_b32_e32 v1, v8, v139
	v_and_b32_e32 v2, 4, v237
	v_and_b32_e32 v137, 24, v238
	v_and_or_b32 v3, v236, s6, v234
	v_lshrrev_b32_e32 v1, 1, v1
	v_or3_b32 v2, v2, v235, v137
	s_movk_i32 s6, 0x60
	v_mul_u32_u24_e32 v9, 0x1600, v3
	v_and_or_b32 v4, v236, s6, v2
	v_or_b32_e32 v3, v1, v9
	v_lshlrev_b32_e32 v128, 1, v3
	v_mul_u32_u24_e32 v3, 0x1600, v4
	v_add_u32_e32 v0, 0x2000, v0
	v_or_b32_e32 v3, v3, v1
	v_lshrrev_b32_e32 v0, 7, v0
	s_movk_i32 s6, 0xf0
	v_lshlrev_b32_e32 v130, 1, v3
	v_and_or_b32 v3, v0, s6, v234
	s_movk_i32 s6, 0xe0
	v_and_or_b32 v0, v0, s6, v2
	v_mul_u32_u24_e32 v0, 0x1600, v0
	s_add_u32 s3, s28, 0xac00000
	v_mul_u32_u24_e32 v10, 0x1600, v3
	v_or_b32_e32 v0, v0, v1
	s_addc_u32 s58, s29, 0
	v_or_b32_e32 v2, v10, v1
	v_lshlrev_b32_e32 v134, 1, v0
	v_lshlrev_b32_e32 v151, 1, v137
	v_and_b32_e32 v0, 0x3c0, v233
	v_and_b32_e32 v1, 32, v138
	s_ashr_i32 s59, s34, 31
	s_ashr_i32 s60, s2, 31
	v_mov_b32_e32 v131, 0
	v_lshlrev_b32_e32 v132, 1, v2
	v_bitop3_b32 v150, v151, v1, v0 bitop3:0x36
	s_cmpk_gt_i32 s2, 0xff
	v_mov_b32_e32 v135, v131
	v_mov_b32_e32 v129, v131
	v_mov_b32_e32 v133, v131
	v_readfirstlane_b32 s6, v231
	s_cbranch_scc1 .LBB0_2383
	s_lshr_b32 s10, s60, 29
	s_add_i32 s10, s2, s10
	s_ashr_i32 s11, s10, 3
	s_and_b32 s10, s10, -8
	s_waitcnt lgkmcnt(0)
	s_lshr_b32 s12, s6, 6
	s_sub_i32 s10, s2, s10
	s_lshr_b32 s7, s6, 8
	s_lshl_b32 s17, s12, 10
	s_lshl_b32 s14, s10, 5
	s_mul_i32 s13, s10, 33
	s_cmp_lt_i32 s10, 0
	s_cselect_b32 s10, s13, s14
	s_add_i32 s10, s10, s11
	s_ashr_i32 s11, s10, 31
	s_lshr_b32 s11, s11, 26
	s_add_i32 s11, s10, s11
	s_ashr_i32 s13, s11, 6
	s_and_b32 s11, s11, 0xffc0
	s_sub_i32 s10, s10, s11
	s_bfe_i32 s11, s10, 0x80000
	s_bfe_u32 s11, s11, 0x3000c
	s_add_i32 s11, s10, s11
	s_lshl_b32 s14, s13, 3
	s_bfe_i32 s13, s11, 0x80000
	s_and_b32 s11, s11, 0xf8
	s_sub_i32 s10, s10, s11
	s_sext_i32_i8 s10, s10
	s_sext_i32_i16 s15, s13
	s_add_i32 s14, s14, s10
	s_lshr_b32 s13, s15, 3
	s_mul_i32 s11, s14, 0x2c0000
	s_mul_hi_i32 s10, s14, 0x2c0000
	s_add_u32 s22, s52, s11
	s_addc_u32 s23, s53, s10
	s_ashr_i32 s10, s15, 3
	s_mul_hi_i32 s11, s10, 0x2c0000
	s_mul_i32 s10, s10, 0x2c0000
	s_add_u32 s24, s3, s10
	s_addc_u32 s25, s58, s11
	s_add_i32 s36, s17, 0
	s_add_i32 m0, s36, 0x10000
	v_lshl_add_u64 v[0:1], s[24:25], 0, v[130:131]
	global_load_lds_dwordx4 v[0:1], off
	s_add_i32 m0, s36, 0x12000
	s_add_u32 s10, s24, 0x160000
	v_lshl_add_u64 v[2:3], s[24:25], 0, v[134:135]
	s_addc_u32 s11, s25, 0
	global_load_lds_dwordx4 v[2:3], off
	s_add_i32 m0, s36, 0x14000
	v_lshl_add_u64 v[4:5], s[10:11], 0, v[130:131]
	global_load_lds_dwordx4 v[4:5], off
	v_lshl_add_u64 v[4:5], s[10:11], 0, v[134:135]
	s_add_i32 m0, s36, 0x16000
	s_add_i32 s37, s36, 0x2000
	global_load_lds_dwordx4 v[4:5], off
	v_lshl_add_u64 v[6:7], s[22:23], 0, v[128:129]
	s_mov_b32 m0, s36
	s_add_u32 s10, s22, 0x160000
	global_load_lds_dwordx4 v[6:7], off
	v_lshl_add_u64 v[4:5], s[22:23], 0, v[132:133]
	s_mov_b32 m0, s37
	s_addc_u32 s11, s23, 0
	s_add_i32 s38, s36, 0x4000
	global_load_lds_dwordx4 v[4:5], off
	v_lshl_add_u64 v[12:13], s[10:11], 0, v[128:129]
	s_mov_b32 m0, s38
	s_add_i32 s39, s36, 0x6000
	global_load_lds_dwordx4 v[12:13], off
	v_lshl_add_u64 v[12:13], s[10:11], 0, v[132:133]
	s_mov_b32 m0, s39
	s_cmp_eq_u32 s7, 1
	global_load_lds_dwordx4 v[12:13], off
	s_cselect_b64 s[10:11], -1, 0
	s_cmp_lg_u32 s7, 1
	s_mov_b32 s40, 0
	s_cbranch_scc1 .LBB0_2366
	s_barrier

.LBB0_2383:
	s_cmpk_gt_i32 s2, 0xaf
	v_readfirstlane_b32 s7, v231
.LBB0_2399:
	s_cmp_gt_i32 s31, 18
	s_cselect_b64 s[6:7], -1, 0
	s_and_b64 s[8:9], s[8:9], s[6:7]
	s_andn2_b64 vcc, exec, s[8:9]
	s_cbranch_vccnz .LBB0_2453
	s_waitcnt vmcnt(0)
	s_waitcnt vmcnt(0) lgkmcnt(0)
	s_barrier
	s_and_saveexec_b64 s[8:9], s[4:5]
	s_cbranch_execz .LBB0_2452
	s_add_i32 s3, 0, 0x20000
	v_mov_b32_e32 v0, s3
	s_waitcnt vmcnt(0) expcnt(0) lgkmcnt(0)
	ds_read_b32 v2, v0
	s_add_i32 s3, 0, 0x20004
	v_mov_b32_e32 v0, s3
	ds_read_b32 v0, v0
	s_waitcnt lgkmcnt(1)
	v_cmp_ne_u32_e32 vcc, 0, v2
	s_cbranch_vccnz .LBB0_2416
	s_add_u32 s4, s28, 0x30300200
	s_addc_u32 s5, s29, 0
	s_add_u32 s10, s28, 0x30300400
	s_addc_u32 s11, s29, 0
	s_add_u32 s12, s28, 0x30300500
	s_addc_u32 s13, s29, 0
	s_add_u32 s14, s28, 0x30300600
	s_addc_u32 s15, s29, 0
	s_add_u32 s16, s28, 0x30300700
	s_addc_u32 s17, s29, 0
	s_add_u32 s18, s28, 0x30300800
	s_addc_u32 s19, s29, 0
	s_add_u32 s20, s28, 0x30300900
	s_addc_u32 s21, s29, 0
	s_add_u32 s22, s28, 0x30300a00
	s_addc_u32 s23, s29, 0
	s_add_u32 s24, s28, 0x30300b00
	s_addc_u32 s25, s29, 0
	s_add_u32 s26, s28, 0x30300c00
	s_addc_u32 s27, s29, 0
	s_add_u32 s36, s28, 0x30300d00
	s_addc_u32 s37, s29, 0
	s_add_u32 s38, s28, 0x30300e00
	s_addc_u32 s39, s29, 0
	s_add_u32 s40, s28, 0x30300f00
	s_addc_u32 s41, s29, 0
	s_add_u32 s42, s28, 0x30301000
	s_addc_u32 s43, s29, 0
	s_add_u32 s44, s28, 0x30301100
	s_addc_u32 s45, s29, 0
	s_add_u32 s46, s28, 0x30301200
	s_addc_u32 s47, s29, 0
	s_mul_i32 s3, s35, s82
	s_add_u32 s50, s28, 0x30301300
	s_mul_i32 s3, s3, s34
	s_addc_u32 s51, s29, 0
	s_mov_b32 s31, 1
	v_mov_b32_e32 v16, 0
	s_branch .LBB0_2404
